# deferred weight transposition: DN(1..3) f32->bf16 transposes moved out of P0 into the idle half round of workgroups 128..255 at the end of the QKV GEMM phases (hand-written tile transposer)
# speedup vs baseline: 1.0022x; 1.0022x over previous
; __device__ __forceinline__ unsigned cvt_pk_bf16(float lo, float hi) { unsigned r; asm volatile("v_cvt_pk_bf16_f32 %0, %1, %2" : "=v"(r) : "v"(lo), "v"(hi)); return r; }
; #define GAS __attribute__((address_space(1)))
; #define LAS __attribute__((address_space(3)))
; #define LDS_WAIT() asm volatile("s_waitcnt lgkmcnt(0)" ::: "memory")
; #define P0_SEG(COUNT, IPM, CALL) if (r < (COUNT) * (IPM)) { const int mi = r / (IPM), item = r % (IPM); (void)mi; CALL; continue; } r -= (COUNT) * (IPM);
; #define P0_UP(mat) p0_transpose_item<1>(A->in[I_FWUP] + (size_t)(mat) * DM * FF2, DM, FF2, WUP + (size_t)(mat) * DM * FF2, scr, item, F.lane, A->in[I_NFFN] + (size_t)(mat) * DM)
; #define P0_DN(mat) p0_transpose_item(A->in[I_FWDN] + (size_t)(mat) * DM * FF, FF, DM, WDN + (size_t)(mat) * DM * FF, scr, item, F.lane)
;     const int nblk = N / 32, kb = item / nblk, nb = item % nblk, k0 = 128 * kb, n0 = 32 * nb;
;     const int nd0 = GLU ? (n0 < 6144 ? 256 * (n0 >> 7) + (n0 & 127) : 256 * ((n0 - 6144) >> 7) + 128 + ((n0 - 6144) & 127)) : n0;
; #pragma unroll 32
;     for (int i = 0; i < 64; ++i) { const int kk = 2 * i + (lane >> 5); scr[kk * 33 + (lane & 31)] = W[(size_t)(k0 + kk) * N + n0 + (lane & 31)]; }
;     LDS_WAIT(); asm volatile("" ::: "memory");
;     const int c = lane & 15;
;     float gk[8];
;     if (gain) load8f(gain + k0 + 8 * c, gk); else {
; #pragma unroll
;         for (int e = 0; e < 8; ++e) gk[e] = 1.0f; }
; #pragma unroll
;     for (int j = 0; j < 8; ++j) { const int n = (lane >> 4) + 4 * j; const LAS float* s = scr + (8 * c) * 33 + n;
;         v4u o; o.x = cvt_pk_bf16(s[0 * 33] * gk[0], s[1 * 33] * gk[1]); o.y = cvt_pk_bf16(s[2 * 33] * gk[2], s[3 * 33] * gk[3]); o.z = cvt_pk_bf16(s[4 * 33] * gk[4], s[5 * 33] * gk[5]); o.w = cvt_pk_bf16(s[6 * 33] * gk[6], s[7 * 33] * gk[7]);
;         *(GAS v4u*)(WT + (size_t)(nd0 + n) * K + k0 + 8 * c) = o; }
;     LDS_WAIT(); asm volatile("" ::: "memory");
; }
; __device__ __forceinline__ void p0_prologue(const Frame& F, CArgs* A, unsigned char* ws) {
;     ...
;     for (int it = F.gw; it < NITEMS; it += F.ngw) {
;         int r = it;
;         P0_SEG(3, IP_DN, P0_DN(3 - mi)) P0_SEG(3, IP_UP, P0_UP(3 - mi))
.LBB0_8:
	s_lshl_b32 s0, s19, 3
	s_add_i32 s18, s0, s10
	s_lshl_b32 s20, s22, 3
	s_cmp_gt_i32 s18, 0xd1ff
	s_cbranch_scc1 .LBB0_76
	s_add_u32 s21, s12, 0x3200000
	s_addc_u32 s40, s13, 0
	s_add_u32 s4, s12, 0x8600000
	s_addc_u32 s5, s13, 0
	s_add_u32 s8, s12, 0x14600000
	s_mul_i32 s0, s10, 0x4400
	v_and_b32_e32 v0, 15, v8
	v_ashrrev_i32_e32 v99, 4, v8
	s_addc_u32 s9, s13, 0
	s_add_i32 s0, s0, 0
	v_and_b32_e32 v12, 31, v8
	v_mov_b32_e32 v15, 0
	v_mul_u32_u24_e32 v1, 0x420, v0
	v_lshlrev_b32_e32 v2, 2, v99
	v_lshlrev_b32_e32 v14, 4, v0
	v_lshl_add_u32 v97, v12, 2, s0
	v_lshlrev_b32_e32 v16, 3, v0
	v_add3_u32 v100, s0, v1, v2
	v_lshl_add_u64 v[0:1], s[12:13], 0, v[14:15]
	s_mov_b64 s[0:1], 0x2200000
	v_lshl_add_u64 v[18:19], v[0:1], 0, s[0:1]
	s_mov_b64 s[0:1], 0x7e00000
	v_lshl_add_u64 v[20:21], v[0:1], 0, s[0:1]
	s_mov_b64 s[0:1], 0x3600000
	v_lshl_add_u64 v[22:23], v[0:1], 0, s[0:1]
	s_mov_b64 s[0:1], 0x2a00000
	v_lshl_add_u64 v[24:25], v[0:1], 0, s[0:1]
	s_mov_b64 s[0:1], 0x1200000
	v_lshl_add_u64 v[26:27], v[0:1], 0, s[0:1]
	s_mov_b64 s[0:1], 0x8200000
	v_lshl_add_u64 v[28:29], v[0:1], 0, s[0:1]
	s_mov_b64 s[0:1], 0x5a00000
	v_lshl_add_u64 v[30:31], v[0:1], 0, s[0:1]
	s_mov_b64 s[0:1], 0x200000
	v_ashrrev_i32_e32 v10, 5, v8
	v_lshl_add_u64 v[32:33], v[0:1], 0, s[0:1]
	s_movk_i32 s0, 0x84
	v_mul_lo_u32 v108, v10, s0
	s_lshl_b32 s0, s19, 8
	s_lshl_b32 s1, s10, 5
	s_add_i32 s41, s0, s1
	s_lshl_b32 s0, s19, 4
	s_lshl_b32 s1, s10, 1
	s_add_i32 s43, s0, s1
	s_lshl_b32 s0, s19, 15
	s_lshl_b32 s1, s10, 12
	s_add_i32 s45, s0, s1
	s_lshl_b32 s0, s19, 16
	s_lshl_b32 s1, s10, 13
	s_mov_b32 s11, 0
	v_add_u32_e32 v101, 4, v99
	v_add_u32_e32 v102, 8, v99
	v_add_u32_e32 v103, 12, v99
	v_add_u32_e32 v104, 16, v99
	v_add_u32_e32 v105, 20, v99
	v_add_u32_e32 v106, 24, v99
	v_add_u32_e32 v107, 28, v99
	v_add_u32_e32 v109, 0x108, v108
	v_add_u32_e32 v110, 0x210, v108
	v_add_u32_e32 v111, 0x318, v108
	v_add_u32_e32 v112, 0x420, v108
	v_add_u32_e32 v113, 0x528, v108
	v_add_u32_e32 v114, 0x630, v108
	v_add_u32_e32 v115, 0x738, v108
	v_add_u32_e32 v116, 0x840, v108
	v_add_u32_e32 v117, 0x948, v108
	v_add_u32_e32 v118, 0xa50, v108
	v_add_u32_e32 v119, 0xb58, v108
	v_add_u32_e32 v120, 0xc60, v108
	v_add_u32_e32 v121, 0xd68, v108
	v_add_u32_e32 v122, 0xe70, v108
	v_add_u32_e32 v123, 0xf78, v108
	v_add_u32_e32 v124, 0x1080, v108
	v_add_u32_e32 v125, 0x1188, v108
	v_add_u32_e32 v126, 0x1290, v108
	v_add_u32_e32 v127, 0x1398, v108
	v_add_u32_e32 v128, 0x14a0, v108
	v_add_u32_e32 v129, 0x15a8, v108
	v_add_u32_e32 v130, 0x16b0, v108
	v_add_u32_e32 v131, 0x17b8, v108
	s_lshl_b32 s42, s22, 8
	s_lshl_b32 s44, s22, 4
	s_lshl_b32 s46, s22, 15
	s_add_i32 s47, s0, s1
	s_lshl_b32 s48, s22, 16
	s_movk_i32 s49, 0x88
	s_mov_b32 s50, 0xc000
	s_movk_i32 s51, 0x3000
	s_mov_b32 s52, 0x9000
	s_mov_b64 s[22:23], 0x2000
	s_movk_i32 s53, 0x2000
	s_mov_b64 s[0:1], 0x1000000
	s_mov_b64 s[26:27], 0x2000000
	s_mov_b64 s[28:29], 0x4000
	s_movk_i32 s54, 0x4000
	s_mov_b64 s[30:31], 0x800000
	s_mov_b64 s[34:35], 0x4800000
	s_mov_b64 s[36:37], 0x6000
	s_movk_i32 s55, 0x6000
	s_mov_b32 s56, s18
	v_add_u32_e32 v132, 0x18c0, v108
	v_add_u32_e32 v133, 0x19c8, v108
	v_add_u32_e32 v134, 0x1ad0, v108
	v_add_u32_e32 v135, 0x1bd8, v108
	v_add_u32_e32 v136, 0x1ce0, v108
	v_add_u32_e32 v137, 0x1de8, v108
	v_add_u32_e32 v138, 0x1ef0, v108
	v_add_u32_e32 v139, 0x1ff8, v108
	v_add_u32_e32 v140, 0x2100, v108
	v_add_u32_e32 v141, 0x2208, v108
	v_add_u32_e32 v142, 0x2310, v108
	v_add_u32_e32 v143, 0x2418, v108
	v_add_u32_e32 v144, 0x2520, v108
	v_add_u32_e32 v145, 0x2628, v108
	v_add_u32_e32 v146, 0x2730, v108
	v_add_u32_e32 v147, 0x2838, v108
	v_add_u32_e32 v148, 0x2940, v108
	v_add_u32_e32 v149, 0x2a48, v108
	v_add_u32_e32 v150, 0x2b50, v108
	v_add_u32_e32 v151, 0x2c58, v108
	v_add_u32_e32 v152, 0x2d60, v108
	v_add_u32_e32 v153, 0x2e68, v108
	v_add_u32_e32 v154, 0x2f70, v108
	v_add_u32_e32 v155, 0x3078, v108
	v_add_u32_e32 v156, 0x3180, v108
	v_add_u32_e32 v157, 0x3288, v108
	v_add_u32_e32 v158, 0x3390, v108
	v_add_u32_e32 v159, 0x3498, v108
	v_add_u32_e32 v160, 0x35a0, v108
	v_add_u32_e32 v161, 0x36a8, v108
	v_add_u32_e32 v162, 0x37b0, v108
	v_add_u32_e32 v163, 0x38b8, v108
	v_add_u32_e32 v164, 0x39c0, v108
	v_add_u32_e32 v165, 0x3ac8, v108
	v_add_u32_e32 v166, 0x3bd0, v108
	v_add_u32_e32 v167, 0x3cd8, v108
	v_add_u32_e32 v168, 0x3de0, v108
	v_add_u32_e32 v169, 0x3ee8, v108
	v_add_u32_e32 v170, 0x3ff0, v108
	v_add_u32_e32 v171, 0x40f8, v108
	v_lshl_add_u64 v[34:35], s[8:9], 0, v[14:15]
	v_lshl_add_u64 v[36:37], s[4:5], 0, v[14:15]
	v_add_u32_e32 v9, 2, v10
	v_add_u32_e32 v11, 6, v10
	v_add_u32_e32 v38, 4, v10
	v_add_u32_e32 v13, 10, v10
	v_add_u32_e32 v40, 8, v10
	v_add_u32_e32 v17, 14, v10
	v_add_u32_e32 v42, 12, v10
	v_add_u32_e32 v39, 18, v10
	v_add_u32_e32 v44, 16, v10
	v_add_u32_e32 v41, 22, v10
	v_add_u32_e32 v46, 20, v10
	v_add_u32_e32 v43, 26, v10
	v_add_u32_e32 v48, 24, v10
	v_add_u32_e32 v45, 30, v10
	v_add_u32_e32 v50, 28, v10
	v_add_u32_e32 v47, 34, v10
	v_add_u32_e32 v52, 32, v10
	v_add_u32_e32 v49, 38, v10
	v_add_u32_e32 v54, 36, v10
	v_add_u32_e32 v51, 42, v10
	v_add_u32_e32 v56, 40, v10
	v_add_u32_e32 v53, 46, v10
	v_add_u32_e32 v58, 44, v10
	v_add_u32_e32 v55, 50, v10
	v_add_u32_e32 v60, 48, v10
	v_add_u32_e32 v57, 54, v10
	v_add_u32_e32 v62, 52, v10
	v_add_u32_e32 v59, 58, v10
	v_add_u32_e32 v64, 56, v10
	v_add_u32_e32 v61, 62, v10
	v_add_u32_e32 v66, 60, v10
	v_add_u32_e32 v63, 0x42, v10
	v_add_u32_e32 v68, 64, v10
	v_add_u32_e32 v65, 0x46, v10
	v_add_u32_e32 v70, 0x44, v10
	v_add_u32_e32 v67, 0x4a, v10
	v_add_u32_e32 v72, 0x48, v10
	v_add_u32_e32 v69, 0x4e, v10
	v_add_u32_e32 v74, 0x4c, v10
	v_add_u32_e32 v71, 0x52, v10
	v_add_u32_e32 v76, 0x50, v10
	v_add_u32_e32 v73, 0x56, v10
	v_add_u32_e32 v78, 0x54, v10
	v_add_u32_e32 v75, 0x5a, v10
	v_add_u32_e32 v80, 0x58, v10
	v_add_u32_e32 v77, 0x5e, v10
	v_add_u32_e32 v82, 0x5c, v10
	v_add_u32_e32 v79, 0x62, v10
	v_add_u32_e32 v84, 0x60, v10
	v_add_u32_e32 v81, 0x66, v10
	v_add_u32_e32 v86, 0x64, v10
	v_add_u32_e32 v83, 0x6a, v10
	v_add_u32_e32 v88, 0x68, v10
	v_add_u32_e32 v85, 0x6e, v10
	v_add_u32_e32 v90, 0x6c, v10
	v_add_u32_e32 v87, 0x72, v10
	v_add_u32_e32 v92, 0x70, v10
	v_add_u32_e32 v89, 0x76, v10
	v_add_u32_e32 v94, 0x74, v10
	v_add_u32_e32 v91, 0x7a, v10
	v_add_u32_e32 v96, 0x78, v10
	v_add_u32_e32 v93, 0x7e, v10
	v_add_u32_e32 v98, 0x7c, v10
	s_cmp_lg_u32 s20, 0x800
	s_cbranch_scc1 .Ldfr_p0all
	s_add_i32 s56, s56, 0x2400
	s_add_i32 s41, s41, 0x48000
	s_add_i32 s43, s43, 0x4800
	s_add_i32 s45, s45, 0x2400000
	s_add_i32 s47, s47, 0x4800000
.Ldfr_p0all:
	s_branch .LBB0_11
.LBB0_10:
	s_add_i32 s56, s56, s20
	s_add_i32 s41, s41, s42
	s_add_i32 s43, s43, s44
	s_add_i32 s45, s45, s46
	s_add_i32 s47, s47, s48
	s_cmp_gt_i32 s56, 0xd1ff
	s_cbranch_scc1 .LBB0_76

; __device__ __forceinline__ unsigned cvt_pk_bf16(float lo, float hi) { unsigned r; asm volatile("v_cvt_pk_bf16_f32 %0, %1, %2" : "=v"(r) : "v"(lo), "v"(hi)); return r; }
; #define GAS __attribute__((address_space(1)))
; #define LAS __attribute__((address_space(3)))
; #define LDS_WAIT() asm volatile("s_waitcnt lgkmcnt(0)" ::: "memory")
;     const int nblk = N / 32, kb = item / nblk, nb = item % nblk, k0 = 128 * kb, n0 = 32 * nb;
;     const int nd0 = GLU ? (n0 < 6144 ? 256 * (n0 >> 7) + (n0 & 127) : 256 * ((n0 - 6144) >> 7) + 128 + ((n0 - 6144) & 127)) : n0;
; #pragma unroll 32
;     for (int i = 0; i < 64; ++i) { const int kk = 2 * i + (lane >> 5); scr[kk * 33 + (lane & 31)] = W[(size_t)(k0 + kk) * N + n0 + (lane & 31)]; }
;     LDS_WAIT(); asm volatile("" ::: "memory");
;     const int c = lane & 15;
;     float gk[8];
;     if (gain) load8f(gain + k0 + 8 * c, gk); else {
; #pragma unroll
;         for (int e = 0; e < 8; ++e) gk[e] = 1.0f; }
; #pragma unroll
;     for (int j = 0; j < 8; ++j) { const int n = (lane >> 4) + 4 * j; const LAS float* s = scr + (8 * c) * 33 + n;
;         v4u o; o.x = cvt_pk_bf16(s[0 * 33] * gk[0], s[1 * 33] * gk[1]); o.y = cvt_pk_bf16(s[2 * 33] * gk[2], s[3 * 33] * gk[3]); o.z = cvt_pk_bf16(s[4 * 33] * gk[4], s[5 * 33] * gk[5]); o.w = cvt_pk_bf16(s[6 * 33] * gk[6], s[7 * 33] * gk[7]);
;         *(GAS v4u*)(WT + (size_t)(nd0 + n) * K + k0 + 8 * c) = o; }
;     LDS_WAIT(); asm volatile("" ::: "memory");
; }
; __global__ void __launch_bounds__(NWAVES * 64, 2) fwd(Args args_unused) {
;     ...
;                 {   constexpr int NU = (MP / 256) * (NQKV / 256); const int rounds = (NU + F.G - 1) / F.G; int c0 = NU - (rounds - 1) * F.G; if (c0 >= F.G) c0 = 0;
;                     if (F.bx >= c0) { Frame F2 = F; F2.bx = F.bx - c0; F2.G = F.G - c0; TQkv fn{P_QS, A->out + O_KVS0, j}; thin_gemm<3>(F2, P_XN + (size_t)MP * DM, DM, 0, Wl, NQKV, DM, fn, P_SSS(2 * layer)); } }
;                 pg8::Gemm g{P_XN, Wl, MP, NQKV, DM, DM, 0}; pg8::StaticOrder So; So.init(MP, NQKV, F.G, F.bx);
;                 pg8::EpiQkv E{P_QKV, P_SSP(2 * layer)};
;                 pg8::gemm_phase<pg8::EpiQkv, pg8::StaticOrder, PG8_ALIGN, PG8_SP2>(ring, g, So, E, F.wave);
.LBB0_1082:
	s_cmp_lg_u32 s83, 0x100
	s_cbranch_scc1 .Ldfr_skip
	s_cmp_lt_u32 s79, 0x80
	s_cbranch_scc1 .Ldfr_skip
	s_mov_b64 s[34:35], exec
	s_mov_b64 exec, -1
	s_load_dwordx2 s[0:1], s[86:87], 0xd8
	s_load_dwordx2 s[2:3], s[86:87], 0xe8
	v_mbcnt_lo_u32_b32 v0, -1, 0
	v_mbcnt_hi_u32_b32 v0, -1, v0
	s_sub_u32 s10, s79, 0x80
	s_lshl_b32 s10, s10, 3
	s_add_u32 s10, s10, s82
	s_mul_i32 s11, s82, 0x4400
	v_readlane_b32 s13, v255, 24
	v_lshrrev_b32_e32 v2, 3, v0
	v_and_b32_e32 v3, 7, v0
	v_lshlrev_b32_e32 v20, 13, v2
	v_lshl_add_u32 v20, v3, 4, v20
	v_add_u32_e32 v21, 0x10000, v20
	v_add_u32_e32 v22, 0x20000, v20
	v_add_u32_e32 v23, 0x30000, v20
	v_add_u32_e32 v24, 0x40000, v20
	v_add_u32_e32 v25, 0x50000, v20
	v_add_u32_e32 v26, 0x60000, v20
	v_add_u32_e32 v27, 0x70000, v20
	v_add_u32_e32 v28, 0x80000, v20
	v_add_u32_e32 v29, 0x90000, v20
	v_add_u32_e32 v30, 0xa0000, v20
	v_add_u32_e32 v31, 0xb0000, v20
	v_add_u32_e32 v32, 0xc0000, v20
	v_add_u32_e32 v33, 0xd0000, v20
	v_add_u32_e32 v34, 0xe0000, v20
	v_add_u32_e32 v35, 0xf0000, v20
	v_mul_u32_u24_e32 v36, 0x84, v2
	v_lshl_add_u32 v36, v3, 4, v36
	v_add_u32_e32 v36, s11, v36
	v_and_b32_e32 v2, 15, v0
	v_lshrrev_b32_e32 v3, 4, v0
	v_mul_u32_u24_e32 v52, 0x420, v2
	v_lshl_add_u32 v52, v3, 2, v52
	v_add_u32_e32 v52, s11, v52
	v_add_u32_e32 v53, 16, v52
	v_add_u32_e32 v54, 32, v52
	v_add_u32_e32 v55, 48, v52
	v_add_u32_e32 v56, 64, v52
	v_add_u32_e32 v57, 80, v52
	v_add_u32_e32 v58, 96, v52
	v_add_u32_e32 v59, 112, v52
	v_mul_u32_u24_e32 v60, 0x3000, v3
	v_lshl_add_u32 v60, v2, 4, v60
	v_add_u32_e32 v61, 0xc000, v60
	v_add_u32_e32 v62, 0x18000, v60
	v_add_u32_e32 v63, 0x24000, v60
	v_add_u32_e32 v64, 0x30000, v60
	v_add_u32_e32 v65, 0x3c000, v60
	v_add_u32_e32 v66, 0x48000, v60
	v_add_u32_e32 v67, 0x54000, v60
	s_waitcnt lgkmcnt(0)
	s_add_u32 s2, s2, 0x14600000
	s_addc_u32 s3, s3, 0
	s_cmp_lg_u32 s13, 0
	s_cbranch_scc1 .Ldfr_p1
	s_mov_b32 s16, s10
	s_lshr_b32 s20, s16, 6
	s_and_b32 s24, s16, 63
	s_lshl_b32 s20, s20, 20
	s_lshl_b32 s24, s24, 7
	s_add_i32 s20, s20, s24
	s_add_i32 s20, s20, 0x6000000
	s_add_u32 s26, s0, s20
	s_addc_u32 s27, s1, 0
	global_load_dwordx4 v[78:81], v20, s[26:27]
	global_load_dwordx4 v[82:85], v21, s[26:27]
	global_load_dwordx4 v[86:89], v22, s[26:27]
	global_load_dwordx4 v[90:93], v23, s[26:27]
	global_load_dwordx4 v[94:97], v24, s[26:27]
	global_load_dwordx4 v[98:101], v25, s[26:27]
	global_load_dwordx4 v[102:105], v26, s[26:27]
	global_load_dwordx4 v[106:109], v27, s[26:27]
	global_load_dwordx4 v[110:113], v28, s[26:27]
	global_load_dwordx4 v[114:117], v29, s[26:27]
	global_load_dwordx4 v[118:121], v30, s[26:27]
	global_load_dwordx4 v[122:125], v31, s[26:27]
	global_load_dwordx4 v[126:129], v32, s[26:27]
	global_load_dwordx4 v[130:133], v33, s[26:27]
	global_load_dwordx4 v[134:137], v34, s[26:27]
	global_load_dwordx4 v[138:141], v35, s[26:27]
	s_add_i32 s16, s10, 0x400
	s_lshr_b32 s20, s16, 6
	s_and_b32 s24, s16, 63
	s_lshl_b32 s20, s20, 20
	s_lshl_b32 s24, s24, 7
	s_add_i32 s20, s20, s24
	s_add_i32 s20, s20, 0x6000000
	s_add_u32 s26, s0, s20
	s_addc_u32 s27, s1, 0
	global_load_dwordx4 v[142:145], v20, s[26:27]
	global_load_dwordx4 v[146:149], v21, s[26:27]
	global_load_dwordx4 v[150:153], v22, s[26:27]
	global_load_dwordx4 v[154:157], v23, s[26:27]
	global_load_dwordx4 v[158:161], v24, s[26:27]
	global_load_dwordx4 v[162:165], v25, s[26:27]
	global_load_dwordx4 v[196:199], v26, s[26:27]
	global_load_dwordx4 v[200:203], v27, s[26:27]
	global_load_dwordx4 v[204:207], v28, s[26:27]
	global_load_dwordx4 v[208:211], v29, s[26:27]
	global_load_dwordx4 v[212:215], v30, s[26:27]
	global_load_dwordx4 v[216:219], v31, s[26:27]
	global_load_dwordx4 v[228:231], v32, s[26:27]
	global_load_dwordx4 v[232:235], v33, s[26:27]
	global_load_dwordx4 v[236:239], v34, s[26:27]
	global_load_dwordx4 v[240:243], v35, s[26:27]
	s_mov_b32 s16, s10
	s_lshr_b32 s20, s16, 6
	s_and_b32 s24, s16, 63
	s_mul_i32 s24, s24, 0x60000
	s_lshl_b32 s20, s20, 8
	s_add_i32 s20, s20, s24
	s_add_i32 s20, s20, 0x3000000
	s_add_u32 s28, s2, s20
	s_addc_u32 s29, s3, 0
	s_waitcnt vmcnt(31)
	ds_write2_b32 v36, v78, v79 offset1:1
	ds_write2_b32 v36, v80, v81 offset0:2 offset1:3
	s_waitcnt vmcnt(30)
	v_add_u32_e32 v49, 0x420, v36
	ds_write2_b32 v49, v82, v83 offset1:1
	ds_write2_b32 v49, v84, v85 offset0:2 offset1:3
	s_waitcnt vmcnt(29)
	v_add_u32_e32 v48, 0x840, v36
	ds_write2_b32 v48, v86, v87 offset1:1
	ds_write2_b32 v48, v88, v89 offset0:2 offset1:3
	s_waitcnt vmcnt(28)
	v_add_u32_e32 v49, 0xc60, v36
	ds_write2_b32 v49, v90, v91 offset1:1
	ds_write2_b32 v49, v92, v93 offset0:2 offset1:3
	s_waitcnt vmcnt(27)
	v_add_u32_e32 v48, 0x1080, v36
	ds_write2_b32 v48, v94, v95 offset1:1
	ds_write2_b32 v48, v96, v97 offset0:2 offset1:3
	s_waitcnt vmcnt(26)
	v_add_u32_e32 v49, 0x14a0, v36
	ds_write2_b32 v49, v98, v99 offset1:1
	ds_write2_b32 v49, v100, v101 offset0:2 offset1:3
	s_waitcnt vmcnt(25)
	v_add_u32_e32 v48, 0x18c0, v36
	ds_write2_b32 v48, v102, v103 offset1:1
	ds_write2_b32 v48, v104, v105 offset0:2 offset1:3
	s_waitcnt vmcnt(24)
	v_add_u32_e32 v49, 0x1ce0, v36
	ds_write2_b32 v49, v106, v107 offset1:1
	ds_write2_b32 v49, v108, v109 offset0:2 offset1:3
	s_waitcnt vmcnt(23)
	v_add_u32_e32 v48, 0x2100, v36
	ds_write2_b32 v48, v110, v111 offset1:1
	ds_write2_b32 v48, v112, v113 offset0:2 offset1:3
	s_waitcnt vmcnt(22)
	v_add_u32_e32 v49, 0x2520, v36
	ds_write2_b32 v49, v114, v115 offset1:1
	ds_write2_b32 v49, v116, v117 offset0:2 offset1:3
	s_waitcnt vmcnt(21)
	v_add_u32_e32 v48, 0x2940, v36
	ds_write2_b32 v48, v118, v119 offset1:1
	ds_write2_b32 v48, v120, v121 offset0:2 offset1:3
	s_waitcnt vmcnt(20)
; __device__ __forceinline__ unsigned cvt_pk_bf16(float lo, float hi) { unsigned r; asm volatile("v_cvt_pk_bf16_f32 %0, %1, %2" : "=v"(r) : "v"(lo), "v"(hi)); return r; }
; #define GAS __attribute__((address_space(1)))
; #define LAS __attribute__((address_space(3)))
; #define LDS_WAIT() asm volatile("s_waitcnt lgkmcnt(0)" ::: "memory")
;     const int nblk = N / 32, kb = item / nblk, nb = item % nblk, k0 = 128 * kb, n0 = 32 * nb;
;     const int nd0 = GLU ? (n0 < 6144 ? 256 * (n0 >> 7) + (n0 & 127) : 256 * ((n0 - 6144) >> 7) + 128 + ((n0 - 6144) & 127)) : n0;
; #pragma unroll 32
;     for (int i = 0; i < 64; ++i) { const int kk = 2 * i + (lane >> 5); scr[kk * 33 + (lane & 31)] = W[(size_t)(k0 + kk) * N + n0 + (lane & 31)]; }
;     LDS_WAIT(); asm volatile("" ::: "memory");
;     const int c = lane & 15;
;     float gk[8];
;     if (gain) load8f(gain + k0 + 8 * c, gk); else {
; #pragma unroll
;         for (int e = 0; e < 8; ++e) gk[e] = 1.0f; }
; #pragma unroll
;     for (int j = 0; j < 8; ++j) { const int n = (lane >> 4) + 4 * j; const LAS float* s = scr + (8 * c) * 33 + n;
;         v4u o; o.x = cvt_pk_bf16(s[0 * 33] * gk[0], s[1 * 33] * gk[1]); o.y = cvt_pk_bf16(s[2 * 33] * gk[2], s[3 * 33] * gk[3]); o.z = cvt_pk_bf16(s[4 * 33] * gk[4], s[5 * 33] * gk[5]); o.w = cvt_pk_bf16(s[6 * 33] * gk[6], s[7 * 33] * gk[7]);
;         *(GAS v4u*)(WT + (size_t)(nd0 + n) * K + k0 + 8 * c) = o; }
;     LDS_WAIT(); asm volatile("" ::: "memory");
; }
	v_add_u32_e32 v49, 0x2d60, v36
	ds_write2_b32 v49, v122, v123 offset1:1
	ds_write2_b32 v49, v124, v125 offset0:2 offset1:3
	s_waitcnt vmcnt(19)
	v_add_u32_e32 v48, 0x3180, v36
	ds_write2_b32 v48, v126, v127 offset1:1
	ds_write2_b32 v48, v128, v129 offset0:2 offset1:3
	s_waitcnt vmcnt(18)
	v_add_u32_e32 v49, 0x35a0, v36
	ds_write2_b32 v49, v130, v131 offset1:1
	ds_write2_b32 v49, v132, v133 offset0:2 offset1:3
	s_waitcnt vmcnt(17)
	v_add_u32_e32 v48, 0x39c0, v36
	ds_write2_b32 v48, v134, v135 offset1:1
	ds_write2_b32 v48, v136, v137 offset0:2 offset1:3
	s_waitcnt vmcnt(16)
	v_add_u32_e32 v49, 0x3de0, v36
	ds_write2_b32 v49, v138, v139 offset1:1
	ds_write2_b32 v49, v140, v141 offset0:2 offset1:3
	ds_read2_b32 v[244:245], v52 offset0:0 offset1:33
	ds_read2_b32 v[246:247], v52 offset0:66 offset1:99
	ds_read2_b32 v[248:249], v52 offset0:132 offset1:165
	ds_read2_b32 v[250:251], v52 offset0:198 offset1:231
	ds_read2_b32 v[38:39], v53 offset0:0 offset1:33
	ds_read2_b32 v[40:41], v53 offset0:66 offset1:99
	ds_read2_b32 v[42:43], v53 offset0:132 offset1:165
	ds_read2_b32 v[44:45], v53 offset0:198 offset1:231
	s_waitcnt lgkmcnt(4)
	v_cvt_pk_bf16_f32 v170, v244, v245
	v_cvt_pk_bf16_f32 v171, v246, v247
	v_cvt_pk_bf16_f32 v172, v248, v249
	v_cvt_pk_bf16_f32 v173, v250, v251
	global_store_dwordx4 v60, v[170:173], s[28:29]
	ds_read2_b32 v[244:245], v54 offset0:0 offset1:33
	ds_read2_b32 v[246:247], v54 offset0:66 offset1:99
	ds_read2_b32 v[248:249], v54 offset0:132 offset1:165
	ds_read2_b32 v[250:251], v54 offset0:198 offset1:231
	s_waitcnt lgkmcnt(4)
	v_cvt_pk_bf16_f32 v176, v38, v39
	v_cvt_pk_bf16_f32 v177, v40, v41
	v_cvt_pk_bf16_f32 v178, v42, v43
	v_cvt_pk_bf16_f32 v179, v44, v45
	global_store_dwordx4 v61, v[176:179], s[28:29]
	ds_read2_b32 v[38:39], v55 offset0:0 offset1:33
	ds_read2_b32 v[40:41], v55 offset0:66 offset1:99
	ds_read2_b32 v[42:43], v55 offset0:132 offset1:165
	ds_read2_b32 v[44:45], v55 offset0:198 offset1:231
	s_waitcnt lgkmcnt(4)
	v_cvt_pk_bf16_f32 v170, v244, v245
	v_cvt_pk_bf16_f32 v171, v246, v247
	v_cvt_pk_bf16_f32 v172, v248, v249
	v_cvt_pk_bf16_f32 v173, v250, v251
	global_store_dwordx4 v62, v[170:173], s[28:29]
	ds_read2_b32 v[244:245], v56 offset0:0 offset1:33
	ds_read2_b32 v[246:247], v56 offset0:66 offset1:99
	ds_read2_b32 v[248:249], v56 offset0:132 offset1:165
	ds_read2_b32 v[250:251], v56 offset0:198 offset1:231
	s_waitcnt lgkmcnt(4)
	v_cvt_pk_bf16_f32 v176, v38, v39
	v_cvt_pk_bf16_f32 v177, v40, v41
	v_cvt_pk_bf16_f32 v178, v42, v43
	v_cvt_pk_bf16_f32 v179, v44, v45
	global_store_dwordx4 v63, v[176:179], s[28:29]
	ds_read2_b32 v[38:39], v57 offset0:0 offset1:33
	ds_read2_b32 v[40:41], v57 offset0:66 offset1:99
	ds_read2_b32 v[42:43], v57 offset0:132 offset1:165
	ds_read2_b32 v[44:45], v57 offset0:198 offset1:231
	s_waitcnt lgkmcnt(4)
	v_cvt_pk_bf16_f32 v170, v244, v245
	v_cvt_pk_bf16_f32 v171, v246, v247
	v_cvt_pk_bf16_f32 v172, v248, v249
	v_cvt_pk_bf16_f32 v173, v250, v251
	global_store_dwordx4 v64, v[170:173], s[28:29]
	ds_read2_b32 v[244:245], v58 offset0:0 offset1:33
	ds_read2_b32 v[246:247], v58 offset0:66 offset1:99
	ds_read2_b32 v[248:249], v58 offset0:132 offset1:165
	ds_read2_b32 v[250:251], v58 offset0:198 offset1:231
	s_waitcnt lgkmcnt(4)
	v_cvt_pk_bf16_f32 v176, v38, v39
	v_cvt_pk_bf16_f32 v177, v40, v41
	v_cvt_pk_bf16_f32 v178, v42, v43
	v_cvt_pk_bf16_f32 v179, v44, v45
	global_store_dwordx4 v65, v[176:179], s[28:29]
	ds_read2_b32 v[38:39], v59 offset0:0 offset1:33
	ds_read2_b32 v[40:41], v59 offset0:66 offset1:99
	ds_read2_b32 v[42:43], v59 offset0:132 offset1:165
	ds_read2_b32 v[44:45], v59 offset0:198 offset1:231
	s_waitcnt lgkmcnt(4)
	v_cvt_pk_bf16_f32 v170, v244, v245
	v_cvt_pk_bf16_f32 v171, v246, v247
	v_cvt_pk_bf16_f32 v172, v248, v249
	v_cvt_pk_bf16_f32 v173, v250, v251
	global_store_dwordx4 v66, v[170:173], s[28:29]
	s_waitcnt lgkmcnt(0)
	v_cvt_pk_bf16_f32 v176, v38, v39
	v_cvt_pk_bf16_f32 v177, v40, v41
	v_cvt_pk_bf16_f32 v178, v42, v43
	v_cvt_pk_bf16_f32 v179, v44, v45
	global_store_dwordx4 v67, v[176:179], s[28:29]
	s_add_i32 s16, s10, 0x800
	s_lshr_b32 s20, s16, 6
	s_and_b32 s24, s16, 63
	s_lshl_b32 s20, s20, 20
	s_lshl_b32 s24, s24, 7
	s_add_i32 s20, s20, s24
	s_add_i32 s20, s20, 0x6000000
	s_add_u32 s26, s0, s20
	s_addc_u32 s27, s1, 0
	global_load_dwordx4 v[78:81], v20, s[26:27]
	global_load_dwordx4 v[82:85], v21, s[26:27]
	global_load_dwordx4 v[86:89], v22, s[26:27]
	global_load_dwordx4 v[90:93], v23, s[26:27]
	global_load_dwordx4 v[94:97], v24, s[26:27]
	global_load_dwordx4 v[98:101], v25, s[26:27]
	global_load_dwordx4 v[102:105], v26, s[26:27]
	global_load_dwordx4 v[106:109], v27, s[26:27]
	global_load_dwordx4 v[110:113], v28, s[26:27]
	global_load_dwordx4 v[114:117], v29, s[26:27]
	global_load_dwordx4 v[118:121], v30, s[26:27]
	global_load_dwordx4 v[122:125], v31, s[26:27]
	global_load_dwordx4 v[126:129], v32, s[26:27]
	global_load_dwordx4 v[130:133], v33, s[26:27]
	global_load_dwordx4 v[134:137], v34, s[26:27]
	global_load_dwordx4 v[138:141], v35, s[26:27]
	s_add_i32 s16, s10, 0x400
	s_lshr_b32 s20, s16, 6
	s_and_b32 s24, s16, 63
	s_mul_i32 s24, s24, 0x60000
	s_lshl_b32 s20, s20, 8
	s_add_i32 s20, s20, s24
	s_add_i32 s20, s20, 0x3000000
	s_add_u32 s28, s2, s20
	s_addc_u32 s29, s3, 0
	s_waitcnt vmcnt(39)
	ds_write2_b32 v36, v142, v143 offset1:1
	ds_write2_b32 v36, v144, v145 offset0:2 offset1:3
	s_waitcnt vmcnt(38)
	v_add_u32_e32 v49, 0x420, v36
	ds_write2_b32 v49, v146, v147 offset1:1
	ds_write2_b32 v49, v148, v149 offset0:2 offset1:3
	s_waitcnt vmcnt(37)
	v_add_u32_e32 v48, 0x840, v36
	ds_write2_b32 v48, v150, v151 offset1:1
	ds_write2_b32 v48, v152, v153 offset0:2 offset1:3
	s_waitcnt vmcnt(36)
; __device__ __forceinline__ unsigned cvt_pk_bf16(float lo, float hi) { unsigned r; asm volatile("v_cvt_pk_bf16_f32 %0, %1, %2" : "=v"(r) : "v"(lo), "v"(hi)); return r; }
; #define GAS __attribute__((address_space(1)))
; #define LAS __attribute__((address_space(3)))
; #define LDS_WAIT() asm volatile("s_waitcnt lgkmcnt(0)" ::: "memory")
;     const int nblk = N / 32, kb = item / nblk, nb = item % nblk, k0 = 128 * kb, n0 = 32 * nb;
;     const int nd0 = GLU ? (n0 < 6144 ? 256 * (n0 >> 7) + (n0 & 127) : 256 * ((n0 - 6144) >> 7) + 128 + ((n0 - 6144) & 127)) : n0;
; #pragma unroll 32
;     for (int i = 0; i < 64; ++i) { const int kk = 2 * i + (lane >> 5); scr[kk * 33 + (lane & 31)] = W[(size_t)(k0 + kk) * N + n0 + (lane & 31)]; }
;     LDS_WAIT(); asm volatile("" ::: "memory");
;     const int c = lane & 15;
;     float gk[8];
;     if (gain) load8f(gain + k0 + 8 * c, gk); else {
; #pragma unroll
;         for (int e = 0; e < 8; ++e) gk[e] = 1.0f; }
; #pragma unroll
;     for (int j = 0; j < 8; ++j) { const int n = (lane >> 4) + 4 * j; const LAS float* s = scr + (8 * c) * 33 + n;
;         v4u o; o.x = cvt_pk_bf16(s[0 * 33] * gk[0], s[1 * 33] * gk[1]); o.y = cvt_pk_bf16(s[2 * 33] * gk[2], s[3 * 33] * gk[3]); o.z = cvt_pk_bf16(s[4 * 33] * gk[4], s[5 * 33] * gk[5]); o.w = cvt_pk_bf16(s[6 * 33] * gk[6], s[7 * 33] * gk[7]);
;         *(GAS v4u*)(WT + (size_t)(nd0 + n) * K + k0 + 8 * c) = o; }
;     LDS_WAIT(); asm volatile("" ::: "memory");
; }
	v_add_u32_e32 v49, 0xc60, v36
	ds_write2_b32 v49, v154, v155 offset1:1
	ds_write2_b32 v49, v156, v157 offset0:2 offset1:3
	s_waitcnt vmcnt(35)
	v_add_u32_e32 v48, 0x1080, v36
	ds_write2_b32 v48, v158, v159 offset1:1
	ds_write2_b32 v48, v160, v161 offset0:2 offset1:3
	s_waitcnt vmcnt(34)
	v_add_u32_e32 v49, 0x14a0, v36
	ds_write2_b32 v49, v162, v163 offset1:1
	ds_write2_b32 v49, v164, v165 offset0:2 offset1:3
	s_waitcnt vmcnt(33)
	v_add_u32_e32 v48, 0x18c0, v36
	ds_write2_b32 v48, v196, v197 offset1:1
	ds_write2_b32 v48, v198, v199 offset0:2 offset1:3
	s_waitcnt vmcnt(32)
	v_add_u32_e32 v49, 0x1ce0, v36
	ds_write2_b32 v49, v200, v201 offset1:1
	ds_write2_b32 v49, v202, v203 offset0:2 offset1:3
	s_waitcnt vmcnt(31)
	v_add_u32_e32 v48, 0x2100, v36
	ds_write2_b32 v48, v204, v205 offset1:1
	ds_write2_b32 v48, v206, v207 offset0:2 offset1:3
	s_waitcnt vmcnt(30)
	v_add_u32_e32 v49, 0x2520, v36
	ds_write2_b32 v49, v208, v209 offset1:1
	ds_write2_b32 v49, v210, v211 offset0:2 offset1:3
	s_waitcnt vmcnt(29)
	v_add_u32_e32 v48, 0x2940, v36
	ds_write2_b32 v48, v212, v213 offset1:1
	ds_write2_b32 v48, v214, v215 offset0:2 offset1:3
	s_waitcnt vmcnt(28)
	v_add_u32_e32 v49, 0x2d60, v36
	ds_write2_b32 v49, v216, v217 offset1:1
	ds_write2_b32 v49, v218, v219 offset0:2 offset1:3
	s_waitcnt vmcnt(27)
	v_add_u32_e32 v48, 0x3180, v36
	ds_write2_b32 v48, v228, v229 offset1:1
	ds_write2_b32 v48, v230, v231 offset0:2 offset1:3
	s_waitcnt vmcnt(26)
	v_add_u32_e32 v49, 0x35a0, v36
	ds_write2_b32 v49, v232, v233 offset1:1
	ds_write2_b32 v49, v234, v235 offset0:2 offset1:3
	s_waitcnt vmcnt(25)
	v_add_u32_e32 v48, 0x39c0, v36
	ds_write2_b32 v48, v236, v237 offset1:1
	ds_write2_b32 v48, v238, v239 offset0:2 offset1:3
	s_waitcnt vmcnt(24)
	v_add_u32_e32 v49, 0x3de0, v36
	ds_write2_b32 v49, v240, v241 offset1:1
	ds_write2_b32 v49, v242, v243 offset0:2 offset1:3
	ds_read2_b32 v[244:245], v52 offset0:0 offset1:33
	ds_read2_b32 v[246:247], v52 offset0:66 offset1:99
	ds_read2_b32 v[248:249], v52 offset0:132 offset1:165
	ds_read2_b32 v[250:251], v52 offset0:198 offset1:231
	ds_read2_b32 v[38:39], v53 offset0:0 offset1:33
	ds_read2_b32 v[40:41], v53 offset0:66 offset1:99
	ds_read2_b32 v[42:43], v53 offset0:132 offset1:165
	ds_read2_b32 v[44:45], v53 offset0:198 offset1:231
	s_waitcnt lgkmcnt(4)
	v_cvt_pk_bf16_f32 v170, v244, v245
	v_cvt_pk_bf16_f32 v171, v246, v247
	v_cvt_pk_bf16_f32 v172, v248, v249
	v_cvt_pk_bf16_f32 v173, v250, v251
	global_store_dwordx4 v60, v[170:173], s[28:29]
	ds_read2_b32 v[244:245], v54 offset0:0 offset1:33
	ds_read2_b32 v[246:247], v54 offset0:66 offset1:99
	ds_read2_b32 v[248:249], v54 offset0:132 offset1:165
	ds_read2_b32 v[250:251], v54 offset0:198 offset1:231
	s_waitcnt lgkmcnt(4)
	v_cvt_pk_bf16_f32 v176, v38, v39
	v_cvt_pk_bf16_f32 v177, v40, v41
	v_cvt_pk_bf16_f32 v178, v42, v43
	v_cvt_pk_bf16_f32 v179, v44, v45
	global_store_dwordx4 v61, v[176:179], s[28:29]
	ds_read2_b32 v[38:39], v55 offset0:0 offset1:33
	ds_read2_b32 v[40:41], v55 offset0:66 offset1:99
	ds_read2_b32 v[42:43], v55 offset0:132 offset1:165
	ds_read2_b32 v[44:45], v55 offset0:198 offset1:231
	s_waitcnt lgkmcnt(4)
	v_cvt_pk_bf16_f32 v170, v244, v245
	v_cvt_pk_bf16_f32 v171, v246, v247
	v_cvt_pk_bf16_f32 v172, v248, v249
	v_cvt_pk_bf16_f32 v173, v250, v251
	global_store_dwordx4 v62, v[170:173], s[28:29]
	ds_read2_b32 v[244:245], v56 offset0:0 offset1:33
	ds_read2_b32 v[246:247], v56 offset0:66 offset1:99
	ds_read2_b32 v[248:249], v56 offset0:132 offset1:165
	ds_read2_b32 v[250:251], v56 offset0:198 offset1:231
	s_waitcnt lgkmcnt(4)
	v_cvt_pk_bf16_f32 v176, v38, v39
	v_cvt_pk_bf16_f32 v177, v40, v41
	v_cvt_pk_bf16_f32 v178, v42, v43
	v_cvt_pk_bf16_f32 v179, v44, v45
	global_store_dwordx4 v63, v[176:179], s[28:29]
	ds_read2_b32 v[38:39], v57 offset0:0 offset1:33
	ds_read2_b32 v[40:41], v57 offset0:66 offset1:99
	ds_read2_b32 v[42:43], v57 offset0:132 offset1:165
	ds_read2_b32 v[44:45], v57 offset0:198 offset1:231
	s_waitcnt lgkmcnt(4)
	v_cvt_pk_bf16_f32 v170, v244, v245
	v_cvt_pk_bf16_f32 v171, v246, v247
	v_cvt_pk_bf16_f32 v172, v248, v249
	v_cvt_pk_bf16_f32 v173, v250, v251
	global_store_dwordx4 v64, v[170:173], s[28:29]
	ds_read2_b32 v[244:245], v58 offset0:0 offset1:33
	ds_read2_b32 v[246:247], v58 offset0:66 offset1:99
	ds_read2_b32 v[248:249], v58 offset0:132 offset1:165
	ds_read2_b32 v[250:251], v58 offset0:198 offset1:231
	s_waitcnt lgkmcnt(4)
	v_cvt_pk_bf16_f32 v176, v38, v39
	v_cvt_pk_bf16_f32 v177, v40, v41
	v_cvt_pk_bf16_f32 v178, v42, v43
	v_cvt_pk_bf16_f32 v179, v44, v45
	global_store_dwordx4 v65, v[176:179], s[28:29]
	ds_read2_b32 v[38:39], v59 offset0:0 offset1:33
	ds_read2_b32 v[40:41], v59 offset0:66 offset1:99
	ds_read2_b32 v[42:43], v59 offset0:132 offset1:165
	ds_read2_b32 v[44:45], v59 offset0:198 offset1:231
	s_waitcnt lgkmcnt(4)
	v_cvt_pk_bf16_f32 v170, v244, v245
	v_cvt_pk_bf16_f32 v171, v246, v247
	v_cvt_pk_bf16_f32 v172, v248, v249
	v_cvt_pk_bf16_f32 v173, v250, v251
	global_store_dwordx4 v66, v[170:173], s[28:29]
	s_waitcnt lgkmcnt(0)
; __device__ __forceinline__ unsigned cvt_pk_bf16(float lo, float hi) { unsigned r; asm volatile("v_cvt_pk_bf16_f32 %0, %1, %2" : "=v"(r) : "v"(lo), "v"(hi)); return r; }
; #define GAS __attribute__((address_space(1)))
; #define LAS __attribute__((address_space(3)))
; #define LDS_WAIT() asm volatile("s_waitcnt lgkmcnt(0)" ::: "memory")
;     const int nblk = N / 32, kb = item / nblk, nb = item % nblk, k0 = 128 * kb, n0 = 32 * nb;
;     const int nd0 = GLU ? (n0 < 6144 ? 256 * (n0 >> 7) + (n0 & 127) : 256 * ((n0 - 6144) >> 7) + 128 + ((n0 - 6144) & 127)) : n0;
; #pragma unroll 32
;     for (int i = 0; i < 64; ++i) { const int kk = 2 * i + (lane >> 5); scr[kk * 33 + (lane & 31)] = W[(size_t)(k0 + kk) * N + n0 + (lane & 31)]; }
;     LDS_WAIT(); asm volatile("" ::: "memory");
;     const int c = lane & 15;
;     float gk[8];
;     if (gain) load8f(gain + k0 + 8 * c, gk); else {
; #pragma unroll
;         for (int e = 0; e < 8; ++e) gk[e] = 1.0f; }
; #pragma unroll
;     for (int j = 0; j < 8; ++j) { const int n = (lane >> 4) + 4 * j; const LAS float* s = scr + (8 * c) * 33 + n;
;         v4u o; o.x = cvt_pk_bf16(s[0 * 33] * gk[0], s[1 * 33] * gk[1]); o.y = cvt_pk_bf16(s[2 * 33] * gk[2], s[3 * 33] * gk[3]); o.z = cvt_pk_bf16(s[4 * 33] * gk[4], s[5 * 33] * gk[5]); o.w = cvt_pk_bf16(s[6 * 33] * gk[6], s[7 * 33] * gk[7]);
;         *(GAS v4u*)(WT + (size_t)(nd0 + n) * K + k0 + 8 * c) = o; }
;     LDS_WAIT(); asm volatile("" ::: "memory");
; }
	v_cvt_pk_bf16_f32 v176, v38, v39
	v_cvt_pk_bf16_f32 v177, v40, v41
	v_cvt_pk_bf16_f32 v178, v42, v43
	v_cvt_pk_bf16_f32 v179, v44, v45
	global_store_dwordx4 v67, v[176:179], s[28:29]
	s_mov_b32 s16, s10
	s_lshr_b32 s20, s16, 6
	s_and_b32 s24, s16, 63
	s_lshl_b32 s20, s20, 20
	s_lshl_b32 s24, s24, 7
	s_add_i32 s20, s20, s24
	s_add_i32 s20, s20, 0x3000000
	s_add_u32 s26, s0, s20
	s_addc_u32 s27, s1, 0
	global_load_dwordx4 v[142:145], v20, s[26:27]
	global_load_dwordx4 v[146:149], v21, s[26:27]
	global_load_dwordx4 v[150:153], v22, s[26:27]
	global_load_dwordx4 v[154:157], v23, s[26:27]
	global_load_dwordx4 v[158:161], v24, s[26:27]
	global_load_dwordx4 v[162:165], v25, s[26:27]
	global_load_dwordx4 v[196:199], v26, s[26:27]
	global_load_dwordx4 v[200:203], v27, s[26:27]
	global_load_dwordx4 v[204:207], v28, s[26:27]
	global_load_dwordx4 v[208:211], v29, s[26:27]
	global_load_dwordx4 v[212:215], v30, s[26:27]
	global_load_dwordx4 v[216:219], v31, s[26:27]
	global_load_dwordx4 v[228:231], v32, s[26:27]
	global_load_dwordx4 v[232:235], v33, s[26:27]
	global_load_dwordx4 v[236:239], v34, s[26:27]
	global_load_dwordx4 v[240:243], v35, s[26:27]
	s_add_i32 s16, s10, 0x800
	s_lshr_b32 s20, s16, 6
	s_and_b32 s24, s16, 63
	s_mul_i32 s24, s24, 0x60000
	s_lshl_b32 s20, s20, 8
	s_add_i32 s20, s20, s24
	s_add_i32 s20, s20, 0x3000000
	s_add_u32 s28, s2, s20
	s_addc_u32 s29, s3, 0
	s_waitcnt vmcnt(39)
	ds_write2_b32 v36, v78, v79 offset1:1
	ds_write2_b32 v36, v80, v81 offset0:2 offset1:3
	s_waitcnt vmcnt(38)
	v_add_u32_e32 v49, 0x420, v36
	ds_write2_b32 v49, v82, v83 offset1:1
	ds_write2_b32 v49, v84, v85 offset0:2 offset1:3
	s_waitcnt vmcnt(37)
	v_add_u32_e32 v48, 0x840, v36
	ds_write2_b32 v48, v86, v87 offset1:1
	ds_write2_b32 v48, v88, v89 offset0:2 offset1:3
	s_waitcnt vmcnt(36)
	v_add_u32_e32 v49, 0xc60, v36
	ds_write2_b32 v49, v90, v91 offset1:1
	ds_write2_b32 v49, v92, v93 offset0:2 offset1:3
	s_waitcnt vmcnt(35)
	v_add_u32_e32 v48, 0x1080, v36
	ds_write2_b32 v48, v94, v95 offset1:1
	ds_write2_b32 v48, v96, v97 offset0:2 offset1:3
	s_waitcnt vmcnt(34)
	v_add_u32_e32 v49, 0x14a0, v36
	ds_write2_b32 v49, v98, v99 offset1:1
	ds_write2_b32 v49, v100, v101 offset0:2 offset1:3
	s_waitcnt vmcnt(33)
	v_add_u32_e32 v48, 0x18c0, v36
	ds_write2_b32 v48, v102, v103 offset1:1
	ds_write2_b32 v48, v104, v105 offset0:2 offset1:3
	s_waitcnt vmcnt(32)
	v_add_u32_e32 v49, 0x1ce0, v36
	ds_write2_b32 v49, v106, v107 offset1:1
	ds_write2_b32 v49, v108, v109 offset0:2 offset1:3
	s_waitcnt vmcnt(31)
	v_add_u32_e32 v48, 0x2100, v36
	ds_write2_b32 v48, v110, v111 offset1:1
	ds_write2_b32 v48, v112, v113 offset0:2 offset1:3
	s_waitcnt vmcnt(30)
	v_add_u32_e32 v49, 0x2520, v36
	ds_write2_b32 v49, v114, v115 offset1:1
	ds_write2_b32 v49, v116, v117 offset0:2 offset1:3
	s_waitcnt vmcnt(29)
	v_add_u32_e32 v48, 0x2940, v36
	ds_write2_b32 v48, v118, v119 offset1:1
	ds_write2_b32 v48, v120, v121 offset0:2 offset1:3
	s_waitcnt vmcnt(28)
	v_add_u32_e32 v49, 0x2d60, v36
	ds_write2_b32 v49, v122, v123 offset1:1
	ds_write2_b32 v49, v124, v125 offset0:2 offset1:3
	s_waitcnt vmcnt(27)
	v_add_u32_e32 v48, 0x3180, v36
	ds_write2_b32 v48, v126, v127 offset1:1
	ds_write2_b32 v48, v128, v129 offset0:2 offset1:3
	s_waitcnt vmcnt(26)
	v_add_u32_e32 v49, 0x35a0, v36
	ds_write2_b32 v49, v130, v131 offset1:1
	ds_write2_b32 v49, v132, v133 offset0:2 offset1:3
	s_waitcnt vmcnt(25)
	v_add_u32_e32 v48, 0x39c0, v36
	ds_write2_b32 v48, v134, v135 offset1:1
	ds_write2_b32 v48, v136, v137 offset0:2 offset1:3
	s_waitcnt vmcnt(24)
	v_add_u32_e32 v49, 0x3de0, v36
	ds_write2_b32 v49, v138, v139 offset1:1
	ds_write2_b32 v49, v140, v141 offset0:2 offset1:3
	ds_read2_b32 v[244:245], v52 offset0:0 offset1:33
	ds_read2_b32 v[246:247], v52 offset0:66 offset1:99
	ds_read2_b32 v[248:249], v52 offset0:132 offset1:165
	ds_read2_b32 v[250:251], v52 offset0:198 offset1:231
	ds_read2_b32 v[38:39], v53 offset0:0 offset1:33
	ds_read2_b32 v[40:41], v53 offset0:66 offset1:99
	ds_read2_b32 v[42:43], v53 offset0:132 offset1:165
	ds_read2_b32 v[44:45], v53 offset0:198 offset1:231
	s_waitcnt lgkmcnt(4)
	v_cvt_pk_bf16_f32 v170, v244, v245
	v_cvt_pk_bf16_f32 v171, v246, v247
	v_cvt_pk_bf16_f32 v172, v248, v249
	v_cvt_pk_bf16_f32 v173, v250, v251
	global_store_dwordx4 v60, v[170:173], s[28:29]
	ds_read2_b32 v[244:245], v54 offset0:0 offset1:33
	ds_read2_b32 v[246:247], v54 offset0:66 offset1:99
	ds_read2_b32 v[248:249], v54 offset0:132 offset1:165
	ds_read2_b32 v[250:251], v54 offset0:198 offset1:231
	s_waitcnt lgkmcnt(4)
	v_cvt_pk_bf16_f32 v176, v38, v39
	v_cvt_pk_bf16_f32 v177, v40, v41
	v_cvt_pk_bf16_f32 v178, v42, v43
	v_cvt_pk_bf16_f32 v179, v44, v45
	global_store_dwordx4 v61, v[176:179], s[28:29]
	ds_read2_b32 v[38:39], v55 offset0:0 offset1:33
	ds_read2_b32 v[40:41], v55 offset0:66 offset1:99
	ds_read2_b32 v[42:43], v55 offset0:132 offset1:165
	ds_read2_b32 v[44:45], v55 offset0:198 offset1:231
	s_waitcnt lgkmcnt(4)
	v_cvt_pk_bf16_f32 v170, v244, v245
	v_cvt_pk_bf16_f32 v171, v246, v247
	v_cvt_pk_bf16_f32 v172, v248, v249
	v_cvt_pk_bf16_f32 v173, v250, v251
	global_store_dwordx4 v62, v[170:173], s[28:29]
	ds_read2_b32 v[244:245], v56 offset0:0 offset1:33
	ds_read2_b32 v[246:247], v56 offset0:66 offset1:99
	ds_read2_b32 v[248:249], v56 offset0:132 offset1:165
	ds_read2_b32 v[250:251], v56 offset0:198 offset1:231
	s_waitcnt lgkmcnt(4)
	v_cvt_pk_bf16_f32 v176, v38, v39
	v_cvt_pk_bf16_f32 v177, v40, v41
	v_cvt_pk_bf16_f32 v178, v42, v43
	v_cvt_pk_bf16_f32 v179, v44, v45
	global_store_dwordx4 v63, v[176:179], s[28:29]
	ds_read2_b32 v[38:39], v57 offset0:0 offset1:33
	ds_read2_b32 v[40:41], v57 offset0:66 offset1:99
	ds_read2_b32 v[42:43], v57 offset0:132 offset1:165
	ds_read2_b32 v[44:45], v57 offset0:198 offset1:231
	s_waitcnt lgkmcnt(4)
; __device__ __forceinline__ unsigned cvt_pk_bf16(float lo, float hi) { unsigned r; asm volatile("v_cvt_pk_bf16_f32 %0, %1, %2" : "=v"(r) : "v"(lo), "v"(hi)); return r; }
; #define GAS __attribute__((address_space(1)))
; #define LAS __attribute__((address_space(3)))
; #define LDS_WAIT() asm volatile("s_waitcnt lgkmcnt(0)" ::: "memory")
;     const int nblk = N / 32, kb = item / nblk, nb = item % nblk, k0 = 128 * kb, n0 = 32 * nb;
;     const int nd0 = GLU ? (n0 < 6144 ? 256 * (n0 >> 7) + (n0 & 127) : 256 * ((n0 - 6144) >> 7) + 128 + ((n0 - 6144) & 127)) : n0;
; #pragma unroll 32
;     for (int i = 0; i < 64; ++i) { const int kk = 2 * i + (lane >> 5); scr[kk * 33 + (lane & 31)] = W[(size_t)(k0 + kk) * N + n0 + (lane & 31)]; }
;     LDS_WAIT(); asm volatile("" ::: "memory");
;     const int c = lane & 15;
;     float gk[8];
;     if (gain) load8f(gain + k0 + 8 * c, gk); else {
; #pragma unroll
;         for (int e = 0; e < 8; ++e) gk[e] = 1.0f; }
; #pragma unroll
;     for (int j = 0; j < 8; ++j) { const int n = (lane >> 4) + 4 * j; const LAS float* s = scr + (8 * c) * 33 + n;
;         v4u o; o.x = cvt_pk_bf16(s[0 * 33] * gk[0], s[1 * 33] * gk[1]); o.y = cvt_pk_bf16(s[2 * 33] * gk[2], s[3 * 33] * gk[3]); o.z = cvt_pk_bf16(s[4 * 33] * gk[4], s[5 * 33] * gk[5]); o.w = cvt_pk_bf16(s[6 * 33] * gk[6], s[7 * 33] * gk[7]);
;         *(GAS v4u*)(WT + (size_t)(nd0 + n) * K + k0 + 8 * c) = o; }
;     LDS_WAIT(); asm volatile("" ::: "memory");
; }
	v_cvt_pk_bf16_f32 v170, v244, v245
	v_cvt_pk_bf16_f32 v171, v246, v247
	v_cvt_pk_bf16_f32 v172, v248, v249
	v_cvt_pk_bf16_f32 v173, v250, v251
	global_store_dwordx4 v64, v[170:173], s[28:29]
	ds_read2_b32 v[244:245], v58 offset0:0 offset1:33
	ds_read2_b32 v[246:247], v58 offset0:66 offset1:99
	ds_read2_b32 v[248:249], v58 offset0:132 offset1:165
	ds_read2_b32 v[250:251], v58 offset0:198 offset1:231
	s_waitcnt lgkmcnt(4)
	v_cvt_pk_bf16_f32 v176, v38, v39
	v_cvt_pk_bf16_f32 v177, v40, v41
	v_cvt_pk_bf16_f32 v178, v42, v43
	v_cvt_pk_bf16_f32 v179, v44, v45
	global_store_dwordx4 v65, v[176:179], s[28:29]
	ds_read2_b32 v[38:39], v59 offset0:0 offset1:33
	ds_read2_b32 v[40:41], v59 offset0:66 offset1:99
	ds_read2_b32 v[42:43], v59 offset0:132 offset1:165
	ds_read2_b32 v[44:45], v59 offset0:198 offset1:231
	s_waitcnt lgkmcnt(4)
	v_cvt_pk_bf16_f32 v170, v244, v245
	v_cvt_pk_bf16_f32 v171, v246, v247
	v_cvt_pk_bf16_f32 v172, v248, v249
	v_cvt_pk_bf16_f32 v173, v250, v251
	global_store_dwordx4 v66, v[170:173], s[28:29]
	s_waitcnt lgkmcnt(0)
	v_cvt_pk_bf16_f32 v176, v38, v39
	v_cvt_pk_bf16_f32 v177, v40, v41
	v_cvt_pk_bf16_f32 v178, v42, v43
	v_cvt_pk_bf16_f32 v179, v44, v45
	global_store_dwordx4 v67, v[176:179], s[28:29]
	s_add_i32 s16, s10, 0x400
	s_lshr_b32 s20, s16, 6
	s_and_b32 s24, s16, 63
	s_lshl_b32 s20, s20, 20
	s_lshl_b32 s24, s24, 7
	s_add_i32 s20, s20, s24
	s_add_i32 s20, s20, 0x3000000
	s_add_u32 s26, s0, s20
	s_addc_u32 s27, s1, 0
	global_load_dwordx4 v[78:81], v20, s[26:27]
	global_load_dwordx4 v[82:85], v21, s[26:27]
	global_load_dwordx4 v[86:89], v22, s[26:27]
	global_load_dwordx4 v[90:93], v23, s[26:27]
	global_load_dwordx4 v[94:97], v24, s[26:27]
	global_load_dwordx4 v[98:101], v25, s[26:27]
	global_load_dwordx4 v[102:105], v26, s[26:27]
	global_load_dwordx4 v[106:109], v27, s[26:27]
	global_load_dwordx4 v[110:113], v28, s[26:27]
	global_load_dwordx4 v[114:117], v29, s[26:27]
	global_load_dwordx4 v[118:121], v30, s[26:27]
	global_load_dwordx4 v[122:125], v31, s[26:27]
	global_load_dwordx4 v[126:129], v32, s[26:27]
	global_load_dwordx4 v[130:133], v33, s[26:27]
	global_load_dwordx4 v[134:137], v34, s[26:27]
	global_load_dwordx4 v[138:141], v35, s[26:27]
	s_mov_b32 s16, s10
	s_lshr_b32 s20, s16, 6
	s_and_b32 s24, s16, 63
	s_mul_i32 s24, s24, 0x60000
	s_lshl_b32 s20, s20, 8
	s_add_i32 s20, s20, s24
	s_add_i32 s20, s20, 0x1800000
	s_add_u32 s28, s2, s20
	s_addc_u32 s29, s3, 0
	s_waitcnt vmcnt(39)
	ds_write2_b32 v36, v142, v143 offset1:1
	ds_write2_b32 v36, v144, v145 offset0:2 offset1:3
	s_waitcnt vmcnt(38)
	v_add_u32_e32 v49, 0x420, v36
	ds_write2_b32 v49, v146, v147 offset1:1
	ds_write2_b32 v49, v148, v149 offset0:2 offset1:3
	s_waitcnt vmcnt(37)
	v_add_u32_e32 v48, 0x840, v36
	ds_write2_b32 v48, v150, v151 offset1:1
	ds_write2_b32 v48, v152, v153 offset0:2 offset1:3
	s_waitcnt vmcnt(36)
	v_add_u32_e32 v49, 0xc60, v36
	ds_write2_b32 v49, v154, v155 offset1:1
	ds_write2_b32 v49, v156, v157 offset0:2 offset1:3
	s_waitcnt vmcnt(35)
	v_add_u32_e32 v48, 0x1080, v36
	ds_write2_b32 v48, v158, v159 offset1:1
	ds_write2_b32 v48, v160, v161 offset0:2 offset1:3
	s_waitcnt vmcnt(34)
	v_add_u32_e32 v49, 0x14a0, v36
	ds_write2_b32 v49, v162, v163 offset1:1
	ds_write2_b32 v49, v164, v165 offset0:2 offset1:3
	s_waitcnt vmcnt(33)
	v_add_u32_e32 v48, 0x18c0, v36
	ds_write2_b32 v48, v196, v197 offset1:1
	ds_write2_b32 v48, v198, v199 offset0:2 offset1:3
	s_waitcnt vmcnt(32)
	v_add_u32_e32 v49, 0x1ce0, v36
	ds_write2_b32 v49, v200, v201 offset1:1
	ds_write2_b32 v49, v202, v203 offset0:2 offset1:3
	s_waitcnt vmcnt(31)
	v_add_u32_e32 v48, 0x2100, v36
	ds_write2_b32 v48, v204, v205 offset1:1
	ds_write2_b32 v48, v206, v207 offset0:2 offset1:3
	s_waitcnt vmcnt(30)
	v_add_u32_e32 v49, 0x2520, v36
	ds_write2_b32 v49, v208, v209 offset1:1
	ds_write2_b32 v49, v210, v211 offset0:2 offset1:3
	s_waitcnt vmcnt(29)
	v_add_u32_e32 v48, 0x2940, v36
	ds_write2_b32 v48, v212, v213 offset1:1
	ds_write2_b32 v48, v214, v215 offset0:2 offset1:3
	s_waitcnt vmcnt(28)
	v_add_u32_e32 v49, 0x2d60, v36
	ds_write2_b32 v49, v216, v217 offset1:1
	ds_write2_b32 v49, v218, v219 offset0:2 offset1:3
	s_waitcnt vmcnt(27)
	v_add_u32_e32 v48, 0x3180, v36
	ds_write2_b32 v48, v228, v229 offset1:1
	ds_write2_b32 v48, v230, v231 offset0:2 offset1:3
	s_waitcnt vmcnt(26)
	v_add_u32_e32 v49, 0x35a0, v36
	ds_write2_b32 v49, v232, v233 offset1:1
	ds_write2_b32 v49, v234, v235 offset0:2 offset1:3
	s_waitcnt vmcnt(25)
	v_add_u32_e32 v48, 0x39c0, v36
	ds_write2_b32 v48, v236, v237 offset1:1
	ds_write2_b32 v48, v238, v239 offset0:2 offset1:3
	s_waitcnt vmcnt(24)
	v_add_u32_e32 v49, 0x3de0, v36
	ds_write2_b32 v49, v240, v241 offset1:1
	ds_write2_b32 v49, v242, v243 offset0:2 offset1:3
	ds_read2_b32 v[244:245], v52 offset0:0 offset1:33
	ds_read2_b32 v[246:247], v52 offset0:66 offset1:99
	ds_read2_b32 v[248:249], v52 offset0:132 offset1:165
	ds_read2_b32 v[250:251], v52 offset0:198 offset1:231
	ds_read2_b32 v[38:39], v53 offset0:0 offset1:33
	ds_read2_b32 v[40:41], v53 offset0:66 offset1:99
	ds_read2_b32 v[42:43], v53 offset0:132 offset1:165
	ds_read2_b32 v[44:45], v53 offset0:198 offset1:231
	s_waitcnt lgkmcnt(4)
	v_cvt_pk_bf16_f32 v170, v244, v245
	v_cvt_pk_bf16_f32 v171, v246, v247
	v_cvt_pk_bf16_f32 v172, v248, v249
	v_cvt_pk_bf16_f32 v173, v250, v251
	global_store_dwordx4 v60, v[170:173], s[28:29]
	ds_read2_b32 v[244:245], v54 offset0:0 offset1:33
	ds_read2_b32 v[246:247], v54 offset0:66 offset1:99
	ds_read2_b32 v[248:249], v54 offset0:132 offset1:165
	ds_read2_b32 v[250:251], v54 offset0:198 offset1:231
	s_waitcnt lgkmcnt(4)
; __device__ __forceinline__ unsigned cvt_pk_bf16(float lo, float hi) { unsigned r; asm volatile("v_cvt_pk_bf16_f32 %0, %1, %2" : "=v"(r) : "v"(lo), "v"(hi)); return r; }
; #define GAS __attribute__((address_space(1)))
; #define LAS __attribute__((address_space(3)))
; #define LDS_WAIT() asm volatile("s_waitcnt lgkmcnt(0)" ::: "memory")
;     const int nblk = N / 32, kb = item / nblk, nb = item % nblk, k0 = 128 * kb, n0 = 32 * nb;
;     const int nd0 = GLU ? (n0 < 6144 ? 256 * (n0 >> 7) + (n0 & 127) : 256 * ((n0 - 6144) >> 7) + 128 + ((n0 - 6144) & 127)) : n0;
; #pragma unroll 32
;     for (int i = 0; i < 64; ++i) { const int kk = 2 * i + (lane >> 5); scr[kk * 33 + (lane & 31)] = W[(size_t)(k0 + kk) * N + n0 + (lane & 31)]; }
;     LDS_WAIT(); asm volatile("" ::: "memory");
;     const int c = lane & 15;
;     float gk[8];
;     if (gain) load8f(gain + k0 + 8 * c, gk); else {
; #pragma unroll
;         for (int e = 0; e < 8; ++e) gk[e] = 1.0f; }
; #pragma unroll
;     for (int j = 0; j < 8; ++j) { const int n = (lane >> 4) + 4 * j; const LAS float* s = scr + (8 * c) * 33 + n;
;         v4u o; o.x = cvt_pk_bf16(s[0 * 33] * gk[0], s[1 * 33] * gk[1]); o.y = cvt_pk_bf16(s[2 * 33] * gk[2], s[3 * 33] * gk[3]); o.z = cvt_pk_bf16(s[4 * 33] * gk[4], s[5 * 33] * gk[5]); o.w = cvt_pk_bf16(s[6 * 33] * gk[6], s[7 * 33] * gk[7]);
;         *(GAS v4u*)(WT + (size_t)(nd0 + n) * K + k0 + 8 * c) = o; }
;     LDS_WAIT(); asm volatile("" ::: "memory");
; }
	v_cvt_pk_bf16_f32 v176, v38, v39
	v_cvt_pk_bf16_f32 v177, v40, v41
	v_cvt_pk_bf16_f32 v178, v42, v43
	v_cvt_pk_bf16_f32 v179, v44, v45
	global_store_dwordx4 v61, v[176:179], s[28:29]
	ds_read2_b32 v[38:39], v55 offset0:0 offset1:33
	ds_read2_b32 v[40:41], v55 offset0:66 offset1:99
	ds_read2_b32 v[42:43], v55 offset0:132 offset1:165
	ds_read2_b32 v[44:45], v55 offset0:198 offset1:231
	s_waitcnt lgkmcnt(4)
	v_cvt_pk_bf16_f32 v170, v244, v245
	v_cvt_pk_bf16_f32 v171, v246, v247
	v_cvt_pk_bf16_f32 v172, v248, v249
	v_cvt_pk_bf16_f32 v173, v250, v251
	global_store_dwordx4 v62, v[170:173], s[28:29]
	ds_read2_b32 v[244:245], v56 offset0:0 offset1:33
	ds_read2_b32 v[246:247], v56 offset0:66 offset1:99
	ds_read2_b32 v[248:249], v56 offset0:132 offset1:165
	ds_read2_b32 v[250:251], v56 offset0:198 offset1:231
	s_waitcnt lgkmcnt(4)
	v_cvt_pk_bf16_f32 v176, v38, v39
	v_cvt_pk_bf16_f32 v177, v40, v41
	v_cvt_pk_bf16_f32 v178, v42, v43
	v_cvt_pk_bf16_f32 v179, v44, v45
	global_store_dwordx4 v63, v[176:179], s[28:29]
	ds_read2_b32 v[38:39], v57 offset0:0 offset1:33
	ds_read2_b32 v[40:41], v57 offset0:66 offset1:99
	ds_read2_b32 v[42:43], v57 offset0:132 offset1:165
	ds_read2_b32 v[44:45], v57 offset0:198 offset1:231
	s_waitcnt lgkmcnt(4)
	v_cvt_pk_bf16_f32 v170, v244, v245
	v_cvt_pk_bf16_f32 v171, v246, v247
	v_cvt_pk_bf16_f32 v172, v248, v249
	v_cvt_pk_bf16_f32 v173, v250, v251
	global_store_dwordx4 v64, v[170:173], s[28:29]
	ds_read2_b32 v[244:245], v58 offset0:0 offset1:33
	ds_read2_b32 v[246:247], v58 offset0:66 offset1:99
	ds_read2_b32 v[248:249], v58 offset0:132 offset1:165
	ds_read2_b32 v[250:251], v58 offset0:198 offset1:231
	s_waitcnt lgkmcnt(4)
	v_cvt_pk_bf16_f32 v176, v38, v39
	v_cvt_pk_bf16_f32 v177, v40, v41
	v_cvt_pk_bf16_f32 v178, v42, v43
	v_cvt_pk_bf16_f32 v179, v44, v45
	global_store_dwordx4 v65, v[176:179], s[28:29]
	ds_read2_b32 v[38:39], v59 offset0:0 offset1:33
	ds_read2_b32 v[40:41], v59 offset0:66 offset1:99
	ds_read2_b32 v[42:43], v59 offset0:132 offset1:165
	ds_read2_b32 v[44:45], v59 offset0:198 offset1:231
	s_waitcnt lgkmcnt(4)
	v_cvt_pk_bf16_f32 v170, v244, v245
	v_cvt_pk_bf16_f32 v171, v246, v247
	v_cvt_pk_bf16_f32 v172, v248, v249
	v_cvt_pk_bf16_f32 v173, v250, v251
	global_store_dwordx4 v66, v[170:173], s[28:29]
	s_waitcnt lgkmcnt(0)
	v_cvt_pk_bf16_f32 v176, v38, v39
	v_cvt_pk_bf16_f32 v177, v40, v41
	v_cvt_pk_bf16_f32 v178, v42, v43
	v_cvt_pk_bf16_f32 v179, v44, v45
	global_store_dwordx4 v67, v[176:179], s[28:29]
	s_add_i32 s16, s10, 0x800
	s_lshr_b32 s20, s16, 6
	s_and_b32 s24, s16, 63
	s_lshl_b32 s20, s20, 20
	s_lshl_b32 s24, s24, 7
	s_add_i32 s20, s20, s24
	s_add_i32 s20, s20, 0x3000000
	s_add_u32 s26, s0, s20
	s_addc_u32 s27, s1, 0
	global_load_dwordx4 v[142:145], v20, s[26:27]
	global_load_dwordx4 v[146:149], v21, s[26:27]
	global_load_dwordx4 v[150:153], v22, s[26:27]
	global_load_dwordx4 v[154:157], v23, s[26:27]
	global_load_dwordx4 v[158:161], v24, s[26:27]
	global_load_dwordx4 v[162:165], v25, s[26:27]
	global_load_dwordx4 v[196:199], v26, s[26:27]
	global_load_dwordx4 v[200:203], v27, s[26:27]
	global_load_dwordx4 v[204:207], v28, s[26:27]
	global_load_dwordx4 v[208:211], v29, s[26:27]
	global_load_dwordx4 v[212:215], v30, s[26:27]
	global_load_dwordx4 v[216:219], v31, s[26:27]
	global_load_dwordx4 v[228:231], v32, s[26:27]
	global_load_dwordx4 v[232:235], v33, s[26:27]
	global_load_dwordx4 v[236:239], v34, s[26:27]
	global_load_dwordx4 v[240:243], v35, s[26:27]
	s_add_i32 s16, s10, 0x400
	s_lshr_b32 s20, s16, 6
	s_and_b32 s24, s16, 63
	s_mul_i32 s24, s24, 0x60000
	s_lshl_b32 s20, s20, 8
	s_add_i32 s20, s20, s24
	s_add_i32 s20, s20, 0x1800000
	s_add_u32 s28, s2, s20
	s_addc_u32 s29, s3, 0
	s_waitcnt vmcnt(39)
	ds_write2_b32 v36, v78, v79 offset1:1
	ds_write2_b32 v36, v80, v81 offset0:2 offset1:3
	s_waitcnt vmcnt(38)
	v_add_u32_e32 v49, 0x420, v36
	ds_write2_b32 v49, v82, v83 offset1:1
	ds_write2_b32 v49, v84, v85 offset0:2 offset1:3
	s_waitcnt vmcnt(37)
	v_add_u32_e32 v48, 0x840, v36
	ds_write2_b32 v48, v86, v87 offset1:1
	ds_write2_b32 v48, v88, v89 offset0:2 offset1:3
	s_waitcnt vmcnt(36)
	v_add_u32_e32 v49, 0xc60, v36
	ds_write2_b32 v49, v90, v91 offset1:1
	ds_write2_b32 v49, v92, v93 offset0:2 offset1:3
	s_waitcnt vmcnt(35)
	v_add_u32_e32 v48, 0x1080, v36
	ds_write2_b32 v48, v94, v95 offset1:1
	ds_write2_b32 v48, v96, v97 offset0:2 offset1:3
	s_waitcnt vmcnt(34)
	v_add_u32_e32 v49, 0x14a0, v36
	ds_write2_b32 v49, v98, v99 offset1:1
	ds_write2_b32 v49, v100, v101 offset0:2 offset1:3
	s_waitcnt vmcnt(33)
	v_add_u32_e32 v48, 0x18c0, v36
	ds_write2_b32 v48, v102, v103 offset1:1
	ds_write2_b32 v48, v104, v105 offset0:2 offset1:3
	s_waitcnt vmcnt(32)
	v_add_u32_e32 v49, 0x1ce0, v36
	ds_write2_b32 v49, v106, v107 offset1:1
	ds_write2_b32 v49, v108, v109 offset0:2 offset1:3
	s_waitcnt vmcnt(31)
	v_add_u32_e32 v48, 0x2100, v36
	ds_write2_b32 v48, v110, v111 offset1:1
	ds_write2_b32 v48, v112, v113 offset0:2 offset1:3
	s_waitcnt vmcnt(30)
	v_add_u32_e32 v49, 0x2520, v36
	ds_write2_b32 v49, v114, v115 offset1:1
	ds_write2_b32 v49, v116, v117 offset0:2 offset1:3
	s_waitcnt vmcnt(29)
	v_add_u32_e32 v48, 0x2940, v36
	ds_write2_b32 v48, v118, v119 offset1:1
	ds_write2_b32 v48, v120, v121 offset0:2 offset1:3
	s_waitcnt vmcnt(28)
	v_add_u32_e32 v49, 0x2d60, v36
	ds_write2_b32 v49, v122, v123 offset1:1
	ds_write2_b32 v49, v124, v125 offset0:2 offset1:3
	s_waitcnt vmcnt(27)
	v_add_u32_e32 v48, 0x3180, v36
	ds_write2_b32 v48, v126, v127 offset1:1
	ds_write2_b32 v48, v128, v129 offset0:2 offset1:3
	s_waitcnt vmcnt(26)
	v_add_u32_e32 v49, 0x35a0, v36
	ds_write2_b32 v49, v130, v131 offset1:1
	ds_write2_b32 v49, v132, v133 offset0:2 offset1:3
	s_waitcnt vmcnt(25)
; __device__ __forceinline__ unsigned cvt_pk_bf16(float lo, float hi) { unsigned r; asm volatile("v_cvt_pk_bf16_f32 %0, %1, %2" : "=v"(r) : "v"(lo), "v"(hi)); return r; }
; #define GAS __attribute__((address_space(1)))
; #define LAS __attribute__((address_space(3)))
; #define LDS_WAIT() asm volatile("s_waitcnt lgkmcnt(0)" ::: "memory")
;     const int nblk = N / 32, kb = item / nblk, nb = item % nblk, k0 = 128 * kb, n0 = 32 * nb;
;     const int nd0 = GLU ? (n0 < 6144 ? 256 * (n0 >> 7) + (n0 & 127) : 256 * ((n0 - 6144) >> 7) + 128 + ((n0 - 6144) & 127)) : n0;
; #pragma unroll 32
;     for (int i = 0; i < 64; ++i) { const int kk = 2 * i + (lane >> 5); scr[kk * 33 + (lane & 31)] = W[(size_t)(k0 + kk) * N + n0 + (lane & 31)]; }
;     LDS_WAIT(); asm volatile("" ::: "memory");
;     const int c = lane & 15;
;     float gk[8];
;     if (gain) load8f(gain + k0 + 8 * c, gk); else {
; #pragma unroll
;         for (int e = 0; e < 8; ++e) gk[e] = 1.0f; }
; #pragma unroll
;     for (int j = 0; j < 8; ++j) { const int n = (lane >> 4) + 4 * j; const LAS float* s = scr + (8 * c) * 33 + n;
;         v4u o; o.x = cvt_pk_bf16(s[0 * 33] * gk[0], s[1 * 33] * gk[1]); o.y = cvt_pk_bf16(s[2 * 33] * gk[2], s[3 * 33] * gk[3]); o.z = cvt_pk_bf16(s[4 * 33] * gk[4], s[5 * 33] * gk[5]); o.w = cvt_pk_bf16(s[6 * 33] * gk[6], s[7 * 33] * gk[7]);
;         *(GAS v4u*)(WT + (size_t)(nd0 + n) * K + k0 + 8 * c) = o; }
;     LDS_WAIT(); asm volatile("" ::: "memory");
; }
	v_add_u32_e32 v48, 0x39c0, v36
	ds_write2_b32 v48, v134, v135 offset1:1
	ds_write2_b32 v48, v136, v137 offset0:2 offset1:3
	s_waitcnt vmcnt(24)
	v_add_u32_e32 v49, 0x3de0, v36
	ds_write2_b32 v49, v138, v139 offset1:1
	ds_write2_b32 v49, v140, v141 offset0:2 offset1:3
	ds_read2_b32 v[244:245], v52 offset0:0 offset1:33
	ds_read2_b32 v[246:247], v52 offset0:66 offset1:99
	ds_read2_b32 v[248:249], v52 offset0:132 offset1:165
	ds_read2_b32 v[250:251], v52 offset0:198 offset1:231
	ds_read2_b32 v[38:39], v53 offset0:0 offset1:33
	ds_read2_b32 v[40:41], v53 offset0:66 offset1:99
	ds_read2_b32 v[42:43], v53 offset0:132 offset1:165
	ds_read2_b32 v[44:45], v53 offset0:198 offset1:231
	s_waitcnt lgkmcnt(4)
	v_cvt_pk_bf16_f32 v170, v244, v245
	v_cvt_pk_bf16_f32 v171, v246, v247
	v_cvt_pk_bf16_f32 v172, v248, v249
	v_cvt_pk_bf16_f32 v173, v250, v251
	global_store_dwordx4 v60, v[170:173], s[28:29]
	ds_read2_b32 v[244:245], v54 offset0:0 offset1:33
	ds_read2_b32 v[246:247], v54 offset0:66 offset1:99
	ds_read2_b32 v[248:249], v54 offset0:132 offset1:165
	ds_read2_b32 v[250:251], v54 offset0:198 offset1:231
	s_waitcnt lgkmcnt(4)
	v_cvt_pk_bf16_f32 v176, v38, v39
	v_cvt_pk_bf16_f32 v177, v40, v41
	v_cvt_pk_bf16_f32 v178, v42, v43
	v_cvt_pk_bf16_f32 v179, v44, v45
	global_store_dwordx4 v61, v[176:179], s[28:29]
	ds_read2_b32 v[38:39], v55 offset0:0 offset1:33
	ds_read2_b32 v[40:41], v55 offset0:66 offset1:99
	ds_read2_b32 v[42:43], v55 offset0:132 offset1:165
	ds_read2_b32 v[44:45], v55 offset0:198 offset1:231
	s_waitcnt lgkmcnt(4)
	v_cvt_pk_bf16_f32 v170, v244, v245
	v_cvt_pk_bf16_f32 v171, v246, v247
	v_cvt_pk_bf16_f32 v172, v248, v249
	v_cvt_pk_bf16_f32 v173, v250, v251
	global_store_dwordx4 v62, v[170:173], s[28:29]
	ds_read2_b32 v[244:245], v56 offset0:0 offset1:33
	ds_read2_b32 v[246:247], v56 offset0:66 offset1:99
	ds_read2_b32 v[248:249], v56 offset0:132 offset1:165
	ds_read2_b32 v[250:251], v56 offset0:198 offset1:231
	s_waitcnt lgkmcnt(4)
	v_cvt_pk_bf16_f32 v176, v38, v39
	v_cvt_pk_bf16_f32 v177, v40, v41
	v_cvt_pk_bf16_f32 v178, v42, v43
	v_cvt_pk_bf16_f32 v179, v44, v45
	global_store_dwordx4 v63, v[176:179], s[28:29]
	ds_read2_b32 v[38:39], v57 offset0:0 offset1:33
	ds_read2_b32 v[40:41], v57 offset0:66 offset1:99
	ds_read2_b32 v[42:43], v57 offset0:132 offset1:165
	ds_read2_b32 v[44:45], v57 offset0:198 offset1:231
	s_waitcnt lgkmcnt(4)
	v_cvt_pk_bf16_f32 v170, v244, v245
	v_cvt_pk_bf16_f32 v171, v246, v247
	v_cvt_pk_bf16_f32 v172, v248, v249
	v_cvt_pk_bf16_f32 v173, v250, v251
	global_store_dwordx4 v64, v[170:173], s[28:29]
	ds_read2_b32 v[244:245], v58 offset0:0 offset1:33
	ds_read2_b32 v[246:247], v58 offset0:66 offset1:99
	ds_read2_b32 v[248:249], v58 offset0:132 offset1:165
	ds_read2_b32 v[250:251], v58 offset0:198 offset1:231
	s_waitcnt lgkmcnt(4)
	v_cvt_pk_bf16_f32 v176, v38, v39
	v_cvt_pk_bf16_f32 v177, v40, v41
	v_cvt_pk_bf16_f32 v178, v42, v43
	v_cvt_pk_bf16_f32 v179, v44, v45
	global_store_dwordx4 v65, v[176:179], s[28:29]
	ds_read2_b32 v[38:39], v59 offset0:0 offset1:33
	ds_read2_b32 v[40:41], v59 offset0:66 offset1:99
	ds_read2_b32 v[42:43], v59 offset0:132 offset1:165
	ds_read2_b32 v[44:45], v59 offset0:198 offset1:231
	s_waitcnt lgkmcnt(4)
	v_cvt_pk_bf16_f32 v170, v244, v245
	v_cvt_pk_bf16_f32 v171, v246, v247
	v_cvt_pk_bf16_f32 v172, v248, v249
	v_cvt_pk_bf16_f32 v173, v250, v251
	global_store_dwordx4 v66, v[170:173], s[28:29]
	s_waitcnt lgkmcnt(0)
	v_cvt_pk_bf16_f32 v176, v38, v39
	v_cvt_pk_bf16_f32 v177, v40, v41
	v_cvt_pk_bf16_f32 v178, v42, v43
	v_cvt_pk_bf16_f32 v179, v44, v45
	global_store_dwordx4 v67, v[176:179], s[28:29]
	s_add_i32 s16, s10, 0x800
	s_lshr_b32 s20, s16, 6
	s_and_b32 s24, s16, 63
	s_mul_i32 s24, s24, 0x60000
	s_lshl_b32 s20, s20, 8
	s_add_i32 s20, s20, s24
	s_add_i32 s20, s20, 0x1800000
	s_add_u32 s28, s2, s20
	s_addc_u32 s29, s3, 0
	s_waitcnt vmcnt(23)
	ds_write2_b32 v36, v142, v143 offset1:1
	ds_write2_b32 v36, v144, v145 offset0:2 offset1:3
	s_waitcnt vmcnt(22)
	v_add_u32_e32 v49, 0x420, v36
	ds_write2_b32 v49, v146, v147 offset1:1
	ds_write2_b32 v49, v148, v149 offset0:2 offset1:3
	s_waitcnt vmcnt(21)
	v_add_u32_e32 v48, 0x840, v36
	ds_write2_b32 v48, v150, v151 offset1:1
	ds_write2_b32 v48, v152, v153 offset0:2 offset1:3
	s_waitcnt vmcnt(20)
	v_add_u32_e32 v49, 0xc60, v36
	ds_write2_b32 v49, v154, v155 offset1:1
	ds_write2_b32 v49, v156, v157 offset0:2 offset1:3
	s_waitcnt vmcnt(19)
	v_add_u32_e32 v48, 0x1080, v36
	ds_write2_b32 v48, v158, v159 offset1:1
	ds_write2_b32 v48, v160, v161 offset0:2 offset1:3
	s_waitcnt vmcnt(18)
	v_add_u32_e32 v49, 0x14a0, v36
	ds_write2_b32 v49, v162, v163 offset1:1
	ds_write2_b32 v49, v164, v165 offset0:2 offset1:3
	s_waitcnt vmcnt(17)
	v_add_u32_e32 v48, 0x18c0, v36
	ds_write2_b32 v48, v196, v197 offset1:1
	ds_write2_b32 v48, v198, v199 offset0:2 offset1:3
	s_waitcnt vmcnt(16)
	v_add_u32_e32 v49, 0x1ce0, v36
	ds_write2_b32 v49, v200, v201 offset1:1
	ds_write2_b32 v49, v202, v203 offset0:2 offset1:3
	s_waitcnt vmcnt(15)
	v_add_u32_e32 v48, 0x2100, v36
	ds_write2_b32 v48, v204, v205 offset1:1
	ds_write2_b32 v48, v206, v207 offset0:2 offset1:3
	s_waitcnt vmcnt(14)
	v_add_u32_e32 v49, 0x2520, v36
	ds_write2_b32 v49, v208, v209 offset1:1
	ds_write2_b32 v49, v210, v211 offset0:2 offset1:3
	s_waitcnt vmcnt(13)
	v_add_u32_e32 v48, 0x2940, v36
	ds_write2_b32 v48, v212, v213 offset1:1
	ds_write2_b32 v48, v214, v215 offset0:2 offset1:3
	s_waitcnt vmcnt(12)
	v_add_u32_e32 v49, 0x2d60, v36
	ds_write2_b32 v49, v216, v217 offset1:1
	ds_write2_b32 v49, v218, v219 offset0:2 offset1:3
	s_waitcnt vmcnt(11)
	v_add_u32_e32 v48, 0x3180, v36
	ds_write2_b32 v48, v228, v229 offset1:1
	ds_write2_b32 v48, v230, v231 offset0:2 offset1:3
	s_waitcnt vmcnt(10)
; __device__ __forceinline__ unsigned cvt_pk_bf16(float lo, float hi) { unsigned r; asm volatile("v_cvt_pk_bf16_f32 %0, %1, %2" : "=v"(r) : "v"(lo), "v"(hi)); return r; }
; #define GAS __attribute__((address_space(1)))
; #define LAS __attribute__((address_space(3)))
; #define LDS_WAIT() asm volatile("s_waitcnt lgkmcnt(0)" ::: "memory")
;     const int nblk = N / 32, kb = item / nblk, nb = item % nblk, k0 = 128 * kb, n0 = 32 * nb;
;     const int nd0 = GLU ? (n0 < 6144 ? 256 * (n0 >> 7) + (n0 & 127) : 256 * ((n0 - 6144) >> 7) + 128 + ((n0 - 6144) & 127)) : n0;
; #pragma unroll 32
;     for (int i = 0; i < 64; ++i) { const int kk = 2 * i + (lane >> 5); scr[kk * 33 + (lane & 31)] = W[(size_t)(k0 + kk) * N + n0 + (lane & 31)]; }
;     LDS_WAIT(); asm volatile("" ::: "memory");
;     const int c = lane & 15;
;     float gk[8];
;     if (gain) load8f(gain + k0 + 8 * c, gk); else {
; #pragma unroll
;         for (int e = 0; e < 8; ++e) gk[e] = 1.0f; }
; #pragma unroll
;     for (int j = 0; j < 8; ++j) { const int n = (lane >> 4) + 4 * j; const LAS float* s = scr + (8 * c) * 33 + n;
;         v4u o; o.x = cvt_pk_bf16(s[0 * 33] * gk[0], s[1 * 33] * gk[1]); o.y = cvt_pk_bf16(s[2 * 33] * gk[2], s[3 * 33] * gk[3]); o.z = cvt_pk_bf16(s[4 * 33] * gk[4], s[5 * 33] * gk[5]); o.w = cvt_pk_bf16(s[6 * 33] * gk[6], s[7 * 33] * gk[7]);
;         *(GAS v4u*)(WT + (size_t)(nd0 + n) * K + k0 + 8 * c) = o; }
;     LDS_WAIT(); asm volatile("" ::: "memory");
; }
	v_add_u32_e32 v49, 0x35a0, v36
	ds_write2_b32 v49, v232, v233 offset1:1
	ds_write2_b32 v49, v234, v235 offset0:2 offset1:3
	s_waitcnt vmcnt(9)
	v_add_u32_e32 v48, 0x39c0, v36
	ds_write2_b32 v48, v236, v237 offset1:1
	ds_write2_b32 v48, v238, v239 offset0:2 offset1:3
	s_waitcnt vmcnt(8)
	v_add_u32_e32 v49, 0x3de0, v36
	ds_write2_b32 v49, v240, v241 offset1:1
	ds_write2_b32 v49, v242, v243 offset0:2 offset1:3
	ds_read2_b32 v[244:245], v52 offset0:0 offset1:33
	ds_read2_b32 v[246:247], v52 offset0:66 offset1:99
	ds_read2_b32 v[248:249], v52 offset0:132 offset1:165
	ds_read2_b32 v[250:251], v52 offset0:198 offset1:231
	ds_read2_b32 v[38:39], v53 offset0:0 offset1:33
	ds_read2_b32 v[40:41], v53 offset0:66 offset1:99
	ds_read2_b32 v[42:43], v53 offset0:132 offset1:165
	ds_read2_b32 v[44:45], v53 offset0:198 offset1:231
	s_waitcnt lgkmcnt(4)
	v_cvt_pk_bf16_f32 v170, v244, v245
	v_cvt_pk_bf16_f32 v171, v246, v247
	v_cvt_pk_bf16_f32 v172, v248, v249
	v_cvt_pk_bf16_f32 v173, v250, v251
	global_store_dwordx4 v60, v[170:173], s[28:29]
	ds_read2_b32 v[244:245], v54 offset0:0 offset1:33
	ds_read2_b32 v[246:247], v54 offset0:66 offset1:99
	ds_read2_b32 v[248:249], v54 offset0:132 offset1:165
	ds_read2_b32 v[250:251], v54 offset0:198 offset1:231
	s_waitcnt lgkmcnt(4)
	v_cvt_pk_bf16_f32 v176, v38, v39
	v_cvt_pk_bf16_f32 v177, v40, v41
	v_cvt_pk_bf16_f32 v178, v42, v43
	v_cvt_pk_bf16_f32 v179, v44, v45
	global_store_dwordx4 v61, v[176:179], s[28:29]
	ds_read2_b32 v[38:39], v55 offset0:0 offset1:33
	ds_read2_b32 v[40:41], v55 offset0:66 offset1:99
	ds_read2_b32 v[42:43], v55 offset0:132 offset1:165
	ds_read2_b32 v[44:45], v55 offset0:198 offset1:231
	s_waitcnt lgkmcnt(4)
	v_cvt_pk_bf16_f32 v170, v244, v245
	v_cvt_pk_bf16_f32 v171, v246, v247
	v_cvt_pk_bf16_f32 v172, v248, v249
	v_cvt_pk_bf16_f32 v173, v250, v251
	global_store_dwordx4 v62, v[170:173], s[28:29]
	ds_read2_b32 v[244:245], v56 offset0:0 offset1:33
	ds_read2_b32 v[246:247], v56 offset0:66 offset1:99
	ds_read2_b32 v[248:249], v56 offset0:132 offset1:165
	ds_read2_b32 v[250:251], v56 offset0:198 offset1:231
	s_waitcnt lgkmcnt(4)
	v_cvt_pk_bf16_f32 v176, v38, v39
	v_cvt_pk_bf16_f32 v177, v40, v41
	v_cvt_pk_bf16_f32 v178, v42, v43
	v_cvt_pk_bf16_f32 v179, v44, v45
	global_store_dwordx4 v63, v[176:179], s[28:29]
	ds_read2_b32 v[38:39], v57 offset0:0 offset1:33
	ds_read2_b32 v[40:41], v57 offset0:66 offset1:99
	ds_read2_b32 v[42:43], v57 offset0:132 offset1:165
	ds_read2_b32 v[44:45], v57 offset0:198 offset1:231
	s_waitcnt lgkmcnt(4)
	v_cvt_pk_bf16_f32 v170, v244, v245
	v_cvt_pk_bf16_f32 v171, v246, v247
	v_cvt_pk_bf16_f32 v172, v248, v249
	v_cvt_pk_bf16_f32 v173, v250, v251
	global_store_dwordx4 v64, v[170:173], s[28:29]
	ds_read2_b32 v[244:245], v58 offset0:0 offset1:33
	ds_read2_b32 v[246:247], v58 offset0:66 offset1:99
	ds_read2_b32 v[248:249], v58 offset0:132 offset1:165
	ds_read2_b32 v[250:251], v58 offset0:198 offset1:231
	s_waitcnt lgkmcnt(4)
	v_cvt_pk_bf16_f32 v176, v38, v39
	v_cvt_pk_bf16_f32 v177, v40, v41
	v_cvt_pk_bf16_f32 v178, v42, v43
	v_cvt_pk_bf16_f32 v179, v44, v45
	global_store_dwordx4 v65, v[176:179], s[28:29]
	ds_read2_b32 v[38:39], v59 offset0:0 offset1:33
	ds_read2_b32 v[40:41], v59 offset0:66 offset1:99
	ds_read2_b32 v[42:43], v59 offset0:132 offset1:165
	ds_read2_b32 v[44:45], v59 offset0:198 offset1:231
	s_waitcnt lgkmcnt(4)
	v_cvt_pk_bf16_f32 v170, v244, v245
	v_cvt_pk_bf16_f32 v171, v246, v247
	v_cvt_pk_bf16_f32 v172, v248, v249
	v_cvt_pk_bf16_f32 v173, v250, v251
	global_store_dwordx4 v66, v[170:173], s[28:29]
	s_waitcnt lgkmcnt(0)
	v_cvt_pk_bf16_f32 v176, v38, v39
	v_cvt_pk_bf16_f32 v177, v40, v41
	v_cvt_pk_bf16_f32 v178, v42, v43
	v_cvt_pk_bf16_f32 v179, v44, v45
	global_store_dwordx4 v67, v[176:179], s[28:29]
	s_branch .Ldfr_done
.Ldfr_p1:
	s_mov_b32 s16, s10
	s_lshr_b32 s20, s16, 6
	s_and_b32 s24, s16, 63
	s_lshl_b32 s20, s20, 20
	s_lshl_b32 s24, s24, 7
	s_add_i32 s20, s20, s24
	s_add_i32 s20, s20, 0x9000000
	s_add_u32 s26, s0, s20
	s_addc_u32 s27, s1, 0
	global_load_dwordx4 v[78:81], v20, s[26:27]
	global_load_dwordx4 v[82:85], v21, s[26:27]
	global_load_dwordx4 v[86:89], v22, s[26:27]
	global_load_dwordx4 v[90:93], v23, s[26:27]
	global_load_dwordx4 v[94:97], v24, s[26:27]
	global_load_dwordx4 v[98:101], v25, s[26:27]
	global_load_dwordx4 v[102:105], v26, s[26:27]
	global_load_dwordx4 v[106:109], v27, s[26:27]
	global_load_dwordx4 v[110:113], v28, s[26:27]
	global_load_dwordx4 v[114:117], v29, s[26:27]
	global_load_dwordx4 v[118:121], v30, s[26:27]
	global_load_dwordx4 v[122:125], v31, s[26:27]
	global_load_dwordx4 v[126:129], v32, s[26:27]
	global_load_dwordx4 v[130:133], v33, s[26:27]
	global_load_dwordx4 v[134:137], v34, s[26:27]
	global_load_dwordx4 v[138:141], v35, s[26:27]
	s_add_i32 s16, s10, 0x400
	s_lshr_b32 s20, s16, 6
	s_and_b32 s24, s16, 63
	s_lshl_b32 s20, s20, 20
	s_lshl_b32 s24, s24, 7
	s_add_i32 s20, s20, s24
	s_add_i32 s20, s20, 0x9000000
	s_add_u32 s26, s0, s20
	s_addc_u32 s27, s1, 0
	global_load_dwordx4 v[142:145], v20, s[26:27]
	global_load_dwordx4 v[146:149], v21, s[26:27]
	global_load_dwordx4 v[150:153], v22, s[26:27]
	global_load_dwordx4 v[154:157], v23, s[26:27]
	global_load_dwordx4 v[158:161], v24, s[26:27]
	global_load_dwordx4 v[162:165], v25, s[26:27]
	global_load_dwordx4 v[196:199], v26, s[26:27]
	global_load_dwordx4 v[200:203], v27, s[26:27]
	global_load_dwordx4 v[204:207], v28, s[26:27]
	global_load_dwordx4 v[208:211], v29, s[26:27]
	global_load_dwordx4 v[212:215], v30, s[26:27]
	global_load_dwordx4 v[216:219], v31, s[26:27]
	global_load_dwordx4 v[228:231], v32, s[26:27]
	global_load_dwordx4 v[232:235], v33, s[26:27]
	global_load_dwordx4 v[236:239], v34, s[26:27]
	global_load_dwordx4 v[240:243], v35, s[26:27]
	s_mov_b32 s16, s10
	s_lshr_b32 s20, s16, 6
	s_and_b32 s24, s16, 63
	s_mul_i32 s24, s24, 0x60000
	s_lshl_b32 s20, s20, 8
	s_add_i32 s20, s20, s24
	s_add_i32 s20, s20, 0x4800000
	s_add_u32 s28, s2, s20
	s_addc_u32 s29, s3, 0
	s_waitcnt vmcnt(31)
; __device__ __forceinline__ unsigned cvt_pk_bf16(float lo, float hi) { unsigned r; asm volatile("v_cvt_pk_bf16_f32 %0, %1, %2" : "=v"(r) : "v"(lo), "v"(hi)); return r; }
; #define GAS __attribute__((address_space(1)))
; #define LAS __attribute__((address_space(3)))
; #define LDS_WAIT() asm volatile("s_waitcnt lgkmcnt(0)" ::: "memory")
;     ...
;     for (int i = 0; i < 64; ++i) { const int kk = 2 * i + (lane >> 5); scr[kk * 33 + (lane & 31)] = W[(size_t)(k0 + kk) * N + n0 + (lane & 31)]; }
;     LDS_WAIT(); asm volatile("" ::: "memory");
;     const int c = lane & 15;
;     float gk[8];
;     if (gain) load8f(gain + k0 + 8 * c, gk); else {
; #pragma unroll
;         for (int e = 0; e < 8; ++e) gk[e] = 1.0f; }
; #pragma unroll
;     for (int j = 0; j < 8; ++j) { const int n = (lane >> 4) + 4 * j; const LAS float* s = scr + (8 * c) * 33 + n;
;         v4u o; o.x = cvt_pk_bf16(s[0 * 33] * gk[0], s[1 * 33] * gk[1]); o.y = cvt_pk_bf16(s[2 * 33] * gk[2], s[3 * 33] * gk[3]); o.z = cvt_pk_bf16(s[4 * 33] * gk[4], s[5 * 33] * gk[5]); o.w = cvt_pk_bf16(s[6 * 33] * gk[6], s[7 * 33] * gk[7]);
;         *(GAS v4u*)(WT + (size_t)(nd0 + n) * K + k0 + 8 * c) = o; }
	ds_write2_b32 v36, v78, v79 offset1:1
	ds_write2_b32 v36, v80, v81 offset0:2 offset1:3
	s_waitcnt vmcnt(30)
	v_add_u32_e32 v49, 0x420, v36
	ds_write2_b32 v49, v82, v83 offset1:1
	ds_write2_b32 v49, v84, v85 offset0:2 offset1:3
	s_waitcnt vmcnt(29)
	v_add_u32_e32 v48, 0x840, v36
	ds_write2_b32 v48, v86, v87 offset1:1
	ds_write2_b32 v48, v88, v89 offset0:2 offset1:3
	s_waitcnt vmcnt(28)
	v_add_u32_e32 v49, 0xc60, v36
	ds_write2_b32 v49, v90, v91 offset1:1
	ds_write2_b32 v49, v92, v93 offset0:2 offset1:3
	s_waitcnt vmcnt(27)
	v_add_u32_e32 v48, 0x1080, v36
	ds_write2_b32 v48, v94, v95 offset1:1
	ds_write2_b32 v48, v96, v97 offset0:2 offset1:3
	s_waitcnt vmcnt(26)
	v_add_u32_e32 v49, 0x14a0, v36
	ds_write2_b32 v49, v98, v99 offset1:1
	ds_write2_b32 v49, v100, v101 offset0:2 offset1:3
	s_waitcnt vmcnt(25)
	v_add_u32_e32 v48, 0x18c0, v36
	ds_write2_b32 v48, v102, v103 offset1:1
	ds_write2_b32 v48, v104, v105 offset0:2 offset1:3
	s_waitcnt vmcnt(24)
	v_add_u32_e32 v49, 0x1ce0, v36
	ds_write2_b32 v49, v106, v107 offset1:1
	ds_write2_b32 v49, v108, v109 offset0:2 offset1:3
	s_waitcnt vmcnt(23)
	v_add_u32_e32 v48, 0x2100, v36
	ds_write2_b32 v48, v110, v111 offset1:1
	ds_write2_b32 v48, v112, v113 offset0:2 offset1:3
	s_waitcnt vmcnt(22)
	v_add_u32_e32 v49, 0x2520, v36
	ds_write2_b32 v49, v114, v115 offset1:1
	ds_write2_b32 v49, v116, v117 offset0:2 offset1:3
	s_waitcnt vmcnt(21)
	v_add_u32_e32 v48, 0x2940, v36
	ds_write2_b32 v48, v118, v119 offset1:1
	ds_write2_b32 v48, v120, v121 offset0:2 offset1:3
	s_waitcnt vmcnt(20)
	v_add_u32_e32 v49, 0x2d60, v36
	ds_write2_b32 v49, v122, v123 offset1:1
	ds_write2_b32 v49, v124, v125 offset0:2 offset1:3
	s_waitcnt vmcnt(19)
	v_add_u32_e32 v48, 0x3180, v36
	ds_write2_b32 v48, v126, v127 offset1:1
	ds_write2_b32 v48, v128, v129 offset0:2 offset1:3
	s_waitcnt vmcnt(18)
	v_add_u32_e32 v49, 0x35a0, v36
	ds_write2_b32 v49, v130, v131 offset1:1
	ds_write2_b32 v49, v132, v133 offset0:2 offset1:3
	s_waitcnt vmcnt(17)
	v_add_u32_e32 v48, 0x39c0, v36
	ds_write2_b32 v48, v134, v135 offset1:1
	ds_write2_b32 v48, v136, v137 offset0:2 offset1:3
	s_waitcnt vmcnt(16)
	v_add_u32_e32 v49, 0x3de0, v36
	ds_write2_b32 v49, v138, v139 offset1:1
	ds_write2_b32 v49, v140, v141 offset0:2 offset1:3
	ds_read2_b32 v[244:245], v52 offset0:0 offset1:33
	ds_read2_b32 v[246:247], v52 offset0:66 offset1:99
	ds_read2_b32 v[248:249], v52 offset0:132 offset1:165
	ds_read2_b32 v[250:251], v52 offset0:198 offset1:231
	ds_read2_b32 v[38:39], v53 offset0:0 offset1:33
	ds_read2_b32 v[40:41], v53 offset0:66 offset1:99
	ds_read2_b32 v[42:43], v53 offset0:132 offset1:165
	ds_read2_b32 v[44:45], v53 offset0:198 offset1:231
	s_waitcnt lgkmcnt(4)
	v_cvt_pk_bf16_f32 v170, v244, v245
	v_cvt_pk_bf16_f32 v171, v246, v247
	v_cvt_pk_bf16_f32 v172, v248, v249
	v_cvt_pk_bf16_f32 v173, v250, v251
	global_store_dwordx4 v60, v[170:173], s[28:29]
	ds_read2_b32 v[244:245], v54 offset0:0 offset1:33
	ds_read2_b32 v[246:247], v54 offset0:66 offset1:99
	ds_read2_b32 v[248:249], v54 offset0:132 offset1:165
	ds_read2_b32 v[250:251], v54 offset0:198 offset1:231
	s_waitcnt lgkmcnt(4)
	v_cvt_pk_bf16_f32 v176, v38, v39
	v_cvt_pk_bf16_f32 v177, v40, v41
	v_cvt_pk_bf16_f32 v178, v42, v43
	v_cvt_pk_bf16_f32 v179, v44, v45
	global_store_dwordx4 v61, v[176:179], s[28:29]
	ds_read2_b32 v[38:39], v55 offset0:0 offset1:33
	ds_read2_b32 v[40:41], v55 offset0:66 offset1:99
	ds_read2_b32 v[42:43], v55 offset0:132 offset1:165
	ds_read2_b32 v[44:45], v55 offset0:198 offset1:231
	s_waitcnt lgkmcnt(4)
	v_cvt_pk_bf16_f32 v170, v244, v245
	v_cvt_pk_bf16_f32 v171, v246, v247
	v_cvt_pk_bf16_f32 v172, v248, v249
	v_cvt_pk_bf16_f32 v173, v250, v251
	global_store_dwordx4 v62, v[170:173], s[28:29]
	ds_read2_b32 v[244:245], v56 offset0:0 offset1:33
	ds_read2_b32 v[246:247], v56 offset0:66 offset1:99
	ds_read2_b32 v[248:249], v56 offset0:132 offset1:165
	ds_read2_b32 v[250:251], v56 offset0:198 offset1:231
	s_waitcnt lgkmcnt(4)
	v_cvt_pk_bf16_f32 v176, v38, v39
	v_cvt_pk_bf16_f32 v177, v40, v41
	v_cvt_pk_bf16_f32 v178, v42, v43
	v_cvt_pk_bf16_f32 v179, v44, v45
	global_store_dwordx4 v63, v[176:179], s[28:29]
	ds_read2_b32 v[38:39], v57 offset0:0 offset1:33
	ds_read2_b32 v[40:41], v57 offset0:66 offset1:99
	ds_read2_b32 v[42:43], v57 offset0:132 offset1:165
	ds_read2_b32 v[44:45], v57 offset0:198 offset1:231
	s_waitcnt lgkmcnt(4)
	v_cvt_pk_bf16_f32 v170, v244, v245
	v_cvt_pk_bf16_f32 v171, v246, v247
	v_cvt_pk_bf16_f32 v172, v248, v249
	v_cvt_pk_bf16_f32 v173, v250, v251
	global_store_dwordx4 v64, v[170:173], s[28:29]
	ds_read2_b32 v[244:245], v58 offset0:0 offset1:33
	ds_read2_b32 v[246:247], v58 offset0:66 offset1:99
	ds_read2_b32 v[248:249], v58 offset0:132 offset1:165
	ds_read2_b32 v[250:251], v58 offset0:198 offset1:231
	s_waitcnt lgkmcnt(4)
	v_cvt_pk_bf16_f32 v176, v38, v39
	v_cvt_pk_bf16_f32 v177, v40, v41
	v_cvt_pk_bf16_f32 v178, v42, v43
	v_cvt_pk_bf16_f32 v179, v44, v45
	global_store_dwordx4 v65, v[176:179], s[28:29]
	ds_read2_b32 v[38:39], v59 offset0:0 offset1:33
	ds_read2_b32 v[40:41], v59 offset0:66 offset1:99
	ds_read2_b32 v[42:43], v59 offset0:132 offset1:165
	ds_read2_b32 v[44:45], v59 offset0:198 offset1:231
	s_waitcnt lgkmcnt(4)
	v_cvt_pk_bf16_f32 v170, v244, v245
	v_cvt_pk_bf16_f32 v171, v246, v247
	v_cvt_pk_bf16_f32 v172, v248, v249
	v_cvt_pk_bf16_f32 v173, v250, v251
	global_store_dwordx4 v66, v[170:173], s[28:29]
	s_waitcnt lgkmcnt(0)
; __device__ __forceinline__ unsigned cvt_pk_bf16(float lo, float hi) { unsigned r; asm volatile("v_cvt_pk_bf16_f32 %0, %1, %2" : "=v"(r) : "v"(lo), "v"(hi)); return r; }
; #define GAS __attribute__((address_space(1)))
; #define LAS __attribute__((address_space(3)))
; #define LDS_WAIT() asm volatile("s_waitcnt lgkmcnt(0)" ::: "memory")
;     ...
;     for (int i = 0; i < 64; ++i) { const int kk = 2 * i + (lane >> 5); scr[kk * 33 + (lane & 31)] = W[(size_t)(k0 + kk) * N + n0 + (lane & 31)]; }
;     LDS_WAIT(); asm volatile("" ::: "memory");
;     const int c = lane & 15;
;     float gk[8];
;     if (gain) load8f(gain + k0 + 8 * c, gk); else {
; #pragma unroll
;         for (int e = 0; e < 8; ++e) gk[e] = 1.0f; }
; #pragma unroll
;     for (int j = 0; j < 8; ++j) { const int n = (lane >> 4) + 4 * j; const LAS float* s = scr + (8 * c) * 33 + n;
;         v4u o; o.x = cvt_pk_bf16(s[0 * 33] * gk[0], s[1 * 33] * gk[1]); o.y = cvt_pk_bf16(s[2 * 33] * gk[2], s[3 * 33] * gk[3]); o.z = cvt_pk_bf16(s[4 * 33] * gk[4], s[5 * 33] * gk[5]); o.w = cvt_pk_bf16(s[6 * 33] * gk[6], s[7 * 33] * gk[7]);
;         *(GAS v4u*)(WT + (size_t)(nd0 + n) * K + k0 + 8 * c) = o; }
	v_cvt_pk_bf16_f32 v176, v38, v39
	v_cvt_pk_bf16_f32 v177, v40, v41
	v_cvt_pk_bf16_f32 v178, v42, v43
	v_cvt_pk_bf16_f32 v179, v44, v45
	global_store_dwordx4 v67, v[176:179], s[28:29]
	s_add_i32 s16, s10, 0x800
	s_lshr_b32 s20, s16, 6
	s_and_b32 s24, s16, 63
	s_lshl_b32 s20, s20, 20
	s_lshl_b32 s24, s24, 7
	s_add_i32 s20, s20, s24
	s_add_i32 s20, s20, 0x9000000
	s_add_u32 s26, s0, s20
	s_addc_u32 s27, s1, 0
	global_load_dwordx4 v[78:81], v20, s[26:27]
	global_load_dwordx4 v[82:85], v21, s[26:27]
	global_load_dwordx4 v[86:89], v22, s[26:27]
	global_load_dwordx4 v[90:93], v23, s[26:27]
	global_load_dwordx4 v[94:97], v24, s[26:27]
	global_load_dwordx4 v[98:101], v25, s[26:27]
	global_load_dwordx4 v[102:105], v26, s[26:27]
	global_load_dwordx4 v[106:109], v27, s[26:27]
	global_load_dwordx4 v[110:113], v28, s[26:27]
	global_load_dwordx4 v[114:117], v29, s[26:27]
	global_load_dwordx4 v[118:121], v30, s[26:27]
	global_load_dwordx4 v[122:125], v31, s[26:27]
	global_load_dwordx4 v[126:129], v32, s[26:27]
	global_load_dwordx4 v[130:133], v33, s[26:27]
	global_load_dwordx4 v[134:137], v34, s[26:27]
	global_load_dwordx4 v[138:141], v35, s[26:27]
	s_add_i32 s16, s10, 0x400
	s_lshr_b32 s20, s16, 6
	s_and_b32 s24, s16, 63
	s_mul_i32 s24, s24, 0x60000
	s_lshl_b32 s20, s20, 8
	s_add_i32 s20, s20, s24
	s_add_i32 s20, s20, 0x4800000
	s_add_u32 s28, s2, s20
	s_addc_u32 s29, s3, 0
	s_waitcnt vmcnt(39)
	ds_write2_b32 v36, v142, v143 offset1:1
	ds_write2_b32 v36, v144, v145 offset0:2 offset1:3
	s_waitcnt vmcnt(38)
	v_add_u32_e32 v49, 0x420, v36
	ds_write2_b32 v49, v146, v147 offset1:1
	ds_write2_b32 v49, v148, v149 offset0:2 offset1:3
	s_waitcnt vmcnt(37)
	v_add_u32_e32 v48, 0x840, v36
	ds_write2_b32 v48, v150, v151 offset1:1
	ds_write2_b32 v48, v152, v153 offset0:2 offset1:3
	s_waitcnt vmcnt(36)
	v_add_u32_e32 v49, 0xc60, v36
	ds_write2_b32 v49, v154, v155 offset1:1
	ds_write2_b32 v49, v156, v157 offset0:2 offset1:3
	s_waitcnt vmcnt(35)
	v_add_u32_e32 v48, 0x1080, v36
	ds_write2_b32 v48, v158, v159 offset1:1
	ds_write2_b32 v48, v160, v161 offset0:2 offset1:3
	s_waitcnt vmcnt(34)
	v_add_u32_e32 v49, 0x14a0, v36
	ds_write2_b32 v49, v162, v163 offset1:1
	ds_write2_b32 v49, v164, v165 offset0:2 offset1:3
	s_waitcnt vmcnt(33)
	v_add_u32_e32 v48, 0x18c0, v36
	ds_write2_b32 v48, v196, v197 offset1:1
	ds_write2_b32 v48, v198, v199 offset0:2 offset1:3
	s_waitcnt vmcnt(32)
	v_add_u32_e32 v49, 0x1ce0, v36
	ds_write2_b32 v49, v200, v201 offset1:1
	ds_write2_b32 v49, v202, v203 offset0:2 offset1:3
	s_waitcnt vmcnt(31)
	v_add_u32_e32 v48, 0x2100, v36
	ds_write2_b32 v48, v204, v205 offset1:1
	ds_write2_b32 v48, v206, v207 offset0:2 offset1:3
	s_waitcnt vmcnt(30)
	v_add_u32_e32 v49, 0x2520, v36
	ds_write2_b32 v49, v208, v209 offset1:1
	ds_write2_b32 v49, v210, v211 offset0:2 offset1:3
	s_waitcnt vmcnt(29)
	v_add_u32_e32 v48, 0x2940, v36
	ds_write2_b32 v48, v212, v213 offset1:1
	ds_write2_b32 v48, v214, v215 offset0:2 offset1:3
	s_waitcnt vmcnt(28)
	v_add_u32_e32 v49, 0x2d60, v36
	ds_write2_b32 v49, v216, v217 offset1:1
	ds_write2_b32 v49, v218, v219 offset0:2 offset1:3
	s_waitcnt vmcnt(27)
	v_add_u32_e32 v48, 0x3180, v36
	ds_write2_b32 v48, v228, v229 offset1:1
	ds_write2_b32 v48, v230, v231 offset0:2 offset1:3
	s_waitcnt vmcnt(26)
	v_add_u32_e32 v49, 0x35a0, v36
	ds_write2_b32 v49, v232, v233 offset1:1
	ds_write2_b32 v49, v234, v235 offset0:2 offset1:3
	s_waitcnt vmcnt(25)
	v_add_u32_e32 v48, 0x39c0, v36
	ds_write2_b32 v48, v236, v237 offset1:1
	ds_write2_b32 v48, v238, v239 offset0:2 offset1:3
	s_waitcnt vmcnt(24)
	v_add_u32_e32 v49, 0x3de0, v36
	ds_write2_b32 v49, v240, v241 offset1:1
	ds_write2_b32 v49, v242, v243 offset0:2 offset1:3
	ds_read2_b32 v[244:245], v52 offset0:0 offset1:33
	ds_read2_b32 v[246:247], v52 offset0:66 offset1:99
	ds_read2_b32 v[248:249], v52 offset0:132 offset1:165
	ds_read2_b32 v[250:251], v52 offset0:198 offset1:231
	ds_read2_b32 v[38:39], v53 offset0:0 offset1:33
	ds_read2_b32 v[40:41], v53 offset0:66 offset1:99
	ds_read2_b32 v[42:43], v53 offset0:132 offset1:165
	ds_read2_b32 v[44:45], v53 offset0:198 offset1:231
	s_waitcnt lgkmcnt(4)
	v_cvt_pk_bf16_f32 v170, v244, v245
	v_cvt_pk_bf16_f32 v171, v246, v247
	v_cvt_pk_bf16_f32 v172, v248, v249
	v_cvt_pk_bf16_f32 v173, v250, v251
	global_store_dwordx4 v60, v[170:173], s[28:29]
	ds_read2_b32 v[244:245], v54 offset0:0 offset1:33
	ds_read2_b32 v[246:247], v54 offset0:66 offset1:99
	ds_read2_b32 v[248:249], v54 offset0:132 offset1:165
	ds_read2_b32 v[250:251], v54 offset0:198 offset1:231
	s_waitcnt lgkmcnt(4)
	v_cvt_pk_bf16_f32 v176, v38, v39
	v_cvt_pk_bf16_f32 v177, v40, v41
	v_cvt_pk_bf16_f32 v178, v42, v43
	v_cvt_pk_bf16_f32 v179, v44, v45
	global_store_dwordx4 v61, v[176:179], s[28:29]
	ds_read2_b32 v[38:39], v55 offset0:0 offset1:33
	ds_read2_b32 v[40:41], v55 offset0:66 offset1:99
	ds_read2_b32 v[42:43], v55 offset0:132 offset1:165
	ds_read2_b32 v[44:45], v55 offset0:198 offset1:231
	s_waitcnt lgkmcnt(4)
	v_cvt_pk_bf16_f32 v170, v244, v245
	v_cvt_pk_bf16_f32 v171, v246, v247
	v_cvt_pk_bf16_f32 v172, v248, v249
	v_cvt_pk_bf16_f32 v173, v250, v251
	global_store_dwordx4 v62, v[170:173], s[28:29]
	ds_read2_b32 v[244:245], v56 offset0:0 offset1:33
	ds_read2_b32 v[246:247], v56 offset0:66 offset1:99
	ds_read2_b32 v[248:249], v56 offset0:132 offset1:165
	ds_read2_b32 v[250:251], v56 offset0:198 offset1:231
	s_waitcnt lgkmcnt(4)
	v_cvt_pk_bf16_f32 v176, v38, v39
	v_cvt_pk_bf16_f32 v177, v40, v41
	v_cvt_pk_bf16_f32 v178, v42, v43
	v_cvt_pk_bf16_f32 v179, v44, v45
	global_store_dwordx4 v63, v[176:179], s[28:29]
	ds_read2_b32 v[38:39], v57 offset0:0 offset1:33
	ds_read2_b32 v[40:41], v57 offset0:66 offset1:99
	ds_read2_b32 v[42:43], v57 offset0:132 offset1:165
	ds_read2_b32 v[44:45], v57 offset0:198 offset1:231
	s_waitcnt lgkmcnt(4)
; __device__ __forceinline__ unsigned cvt_pk_bf16(float lo, float hi) { unsigned r; asm volatile("v_cvt_pk_bf16_f32 %0, %1, %2" : "=v"(r) : "v"(lo), "v"(hi)); return r; }
; #define GAS __attribute__((address_space(1)))
; #define LAS __attribute__((address_space(3)))
; #define LDS_WAIT() asm volatile("s_waitcnt lgkmcnt(0)" ::: "memory")
;     ...
;     for (int i = 0; i < 64; ++i) { const int kk = 2 * i + (lane >> 5); scr[kk * 33 + (lane & 31)] = W[(size_t)(k0 + kk) * N + n0 + (lane & 31)]; }
;     LDS_WAIT(); asm volatile("" ::: "memory");
;     const int c = lane & 15;
;     float gk[8];
;     if (gain) load8f(gain + k0 + 8 * c, gk); else {
; #pragma unroll
;         for (int e = 0; e < 8; ++e) gk[e] = 1.0f; }
; #pragma unroll
;     for (int j = 0; j < 8; ++j) { const int n = (lane >> 4) + 4 * j; const LAS float* s = scr + (8 * c) * 33 + n;
;         v4u o; o.x = cvt_pk_bf16(s[0 * 33] * gk[0], s[1 * 33] * gk[1]); o.y = cvt_pk_bf16(s[2 * 33] * gk[2], s[3 * 33] * gk[3]); o.z = cvt_pk_bf16(s[4 * 33] * gk[4], s[5 * 33] * gk[5]); o.w = cvt_pk_bf16(s[6 * 33] * gk[6], s[7 * 33] * gk[7]);
;         *(GAS v4u*)(WT + (size_t)(nd0 + n) * K + k0 + 8 * c) = o; }
	v_cvt_pk_bf16_f32 v170, v244, v245
	v_cvt_pk_bf16_f32 v171, v246, v247
	v_cvt_pk_bf16_f32 v172, v248, v249
	v_cvt_pk_bf16_f32 v173, v250, v251
	global_store_dwordx4 v64, v[170:173], s[28:29]
	ds_read2_b32 v[244:245], v58 offset0:0 offset1:33
	ds_read2_b32 v[246:247], v58 offset0:66 offset1:99
	ds_read2_b32 v[248:249], v58 offset0:132 offset1:165
	ds_read2_b32 v[250:251], v58 offset0:198 offset1:231
	s_waitcnt lgkmcnt(4)
	v_cvt_pk_bf16_f32 v176, v38, v39
	v_cvt_pk_bf16_f32 v177, v40, v41
	v_cvt_pk_bf16_f32 v178, v42, v43
	v_cvt_pk_bf16_f32 v179, v44, v45
	global_store_dwordx4 v65, v[176:179], s[28:29]
	ds_read2_b32 v[38:39], v59 offset0:0 offset1:33
	ds_read2_b32 v[40:41], v59 offset0:66 offset1:99
	ds_read2_b32 v[42:43], v59 offset0:132 offset1:165
	ds_read2_b32 v[44:45], v59 offset0:198 offset1:231
	s_waitcnt lgkmcnt(4)
	v_cvt_pk_bf16_f32 v170, v244, v245
	v_cvt_pk_bf16_f32 v171, v246, v247
	v_cvt_pk_bf16_f32 v172, v248, v249
	v_cvt_pk_bf16_f32 v173, v250, v251
	global_store_dwordx4 v66, v[170:173], s[28:29]
	s_waitcnt lgkmcnt(0)
	v_cvt_pk_bf16_f32 v176, v38, v39
	v_cvt_pk_bf16_f32 v177, v40, v41
	v_cvt_pk_bf16_f32 v178, v42, v43
	v_cvt_pk_bf16_f32 v179, v44, v45
	global_store_dwordx4 v67, v[176:179], s[28:29]
	s_add_i32 s16, s10, 0x800
	s_lshr_b32 s20, s16, 6
	s_and_b32 s24, s16, 63
	s_mul_i32 s24, s24, 0x60000
	s_lshl_b32 s20, s20, 8
	s_add_i32 s20, s20, s24
	s_add_i32 s20, s20, 0x4800000
	s_add_u32 s28, s2, s20
	s_addc_u32 s29, s3, 0
	s_waitcnt vmcnt(23)
	ds_write2_b32 v36, v78, v79 offset1:1
	ds_write2_b32 v36, v80, v81 offset0:2 offset1:3
	s_waitcnt vmcnt(22)
	v_add_u32_e32 v49, 0x420, v36
	ds_write2_b32 v49, v82, v83 offset1:1
	ds_write2_b32 v49, v84, v85 offset0:2 offset1:3
	s_waitcnt vmcnt(21)
	v_add_u32_e32 v48, 0x840, v36
	ds_write2_b32 v48, v86, v87 offset1:1
	ds_write2_b32 v48, v88, v89 offset0:2 offset1:3
	s_waitcnt vmcnt(20)
	v_add_u32_e32 v49, 0xc60, v36
	ds_write2_b32 v49, v90, v91 offset1:1
	ds_write2_b32 v49, v92, v93 offset0:2 offset1:3
	s_waitcnt vmcnt(19)
	v_add_u32_e32 v48, 0x1080, v36
	ds_write2_b32 v48, v94, v95 offset1:1
	ds_write2_b32 v48, v96, v97 offset0:2 offset1:3
	s_waitcnt vmcnt(18)
	v_add_u32_e32 v49, 0x14a0, v36
	ds_write2_b32 v49, v98, v99 offset1:1
	ds_write2_b32 v49, v100, v101 offset0:2 offset1:3
	s_waitcnt vmcnt(17)
	v_add_u32_e32 v48, 0x18c0, v36
	ds_write2_b32 v48, v102, v103 offset1:1
	ds_write2_b32 v48, v104, v105 offset0:2 offset1:3
	s_waitcnt vmcnt(16)
	v_add_u32_e32 v49, 0x1ce0, v36
	ds_write2_b32 v49, v106, v107 offset1:1
	ds_write2_b32 v49, v108, v109 offset0:2 offset1:3
	s_waitcnt vmcnt(15)
	v_add_u32_e32 v48, 0x2100, v36
	ds_write2_b32 v48, v110, v111 offset1:1
	ds_write2_b32 v48, v112, v113 offset0:2 offset1:3
	s_waitcnt vmcnt(14)
	v_add_u32_e32 v49, 0x2520, v36
	ds_write2_b32 v49, v114, v115 offset1:1
	ds_write2_b32 v49, v116, v117 offset0:2 offset1:3
	s_waitcnt vmcnt(13)
	v_add_u32_e32 v48, 0x2940, v36
	ds_write2_b32 v48, v118, v119 offset1:1
	ds_write2_b32 v48, v120, v121 offset0:2 offset1:3
	s_waitcnt vmcnt(12)
	v_add_u32_e32 v49, 0x2d60, v36
	ds_write2_b32 v49, v122, v123 offset1:1
	ds_write2_b32 v49, v124, v125 offset0:2 offset1:3
	s_waitcnt vmcnt(11)
	v_add_u32_e32 v48, 0x3180, v36
	ds_write2_b32 v48, v126, v127 offset1:1
	ds_write2_b32 v48, v128, v129 offset0:2 offset1:3
	s_waitcnt vmcnt(10)
	v_add_u32_e32 v49, 0x35a0, v36
	ds_write2_b32 v49, v130, v131 offset1:1
	ds_write2_b32 v49, v132, v133 offset0:2 offset1:3
	s_waitcnt vmcnt(9)
	v_add_u32_e32 v48, 0x39c0, v36
	ds_write2_b32 v48, v134, v135 offset1:1
	ds_write2_b32 v48, v136, v137 offset0:2 offset1:3
	s_waitcnt vmcnt(8)
; __device__ __forceinline__ unsigned cvt_pk_bf16(float lo, float hi) { unsigned r; asm volatile("v_cvt_pk_bf16_f32 %0, %1, %2" : "=v"(r) : "v"(lo), "v"(hi)); return r; }
; #define GAS __attribute__((address_space(1)))
; #define LAS __attribute__((address_space(3)))
; #define LDS_WAIT() asm volatile("s_waitcnt lgkmcnt(0)" ::: "memory")
;     ...
;     for (int i = 0; i < 64; ++i) { const int kk = 2 * i + (lane >> 5); scr[kk * 33 + (lane & 31)] = W[(size_t)(k0 + kk) * N + n0 + (lane & 31)]; }
;     LDS_WAIT(); asm volatile("" ::: "memory");
;     const int c = lane & 15;
;     float gk[8];
;     if (gain) load8f(gain + k0 + 8 * c, gk); else {
; #pragma unroll
;         for (int e = 0; e < 8; ++e) gk[e] = 1.0f; }
; #pragma unroll
;     for (int j = 0; j < 8; ++j) { const int n = (lane >> 4) + 4 * j; const LAS float* s = scr + (8 * c) * 33 + n;
;         v4u o; o.x = cvt_pk_bf16(s[0 * 33] * gk[0], s[1 * 33] * gk[1]); o.y = cvt_pk_bf16(s[2 * 33] * gk[2], s[3 * 33] * gk[3]); o.z = cvt_pk_bf16(s[4 * 33] * gk[4], s[5 * 33] * gk[5]); o.w = cvt_pk_bf16(s[6 * 33] * gk[6], s[7 * 33] * gk[7]);
;         *(GAS v4u*)(WT + (size_t)(nd0 + n) * K + k0 + 8 * c) = o; }
	v_add_u32_e32 v49, 0x3de0, v36
	ds_write2_b32 v49, v138, v139 offset1:1
	ds_write2_b32 v49, v140, v141 offset0:2 offset1:3
	ds_read2_b32 v[244:245], v52 offset0:0 offset1:33
	ds_read2_b32 v[246:247], v52 offset0:66 offset1:99
	ds_read2_b32 v[248:249], v52 offset0:132 offset1:165
	ds_read2_b32 v[250:251], v52 offset0:198 offset1:231
	ds_read2_b32 v[38:39], v53 offset0:0 offset1:33
	ds_read2_b32 v[40:41], v53 offset0:66 offset1:99
	ds_read2_b32 v[42:43], v53 offset0:132 offset1:165
	ds_read2_b32 v[44:45], v53 offset0:198 offset1:231
	s_waitcnt lgkmcnt(4)
	v_cvt_pk_bf16_f32 v170, v244, v245
	v_cvt_pk_bf16_f32 v171, v246, v247
	v_cvt_pk_bf16_f32 v172, v248, v249
	v_cvt_pk_bf16_f32 v173, v250, v251
	global_store_dwordx4 v60, v[170:173], s[28:29]
	ds_read2_b32 v[244:245], v54 offset0:0 offset1:33
	ds_read2_b32 v[246:247], v54 offset0:66 offset1:99
	ds_read2_b32 v[248:249], v54 offset0:132 offset1:165
	ds_read2_b32 v[250:251], v54 offset0:198 offset1:231
	s_waitcnt lgkmcnt(4)
	v_cvt_pk_bf16_f32 v176, v38, v39
	v_cvt_pk_bf16_f32 v177, v40, v41
	v_cvt_pk_bf16_f32 v178, v42, v43
	v_cvt_pk_bf16_f32 v179, v44, v45
	global_store_dwordx4 v61, v[176:179], s[28:29]
	ds_read2_b32 v[38:39], v55 offset0:0 offset1:33
	ds_read2_b32 v[40:41], v55 offset0:66 offset1:99
	ds_read2_b32 v[42:43], v55 offset0:132 offset1:165
	ds_read2_b32 v[44:45], v55 offset0:198 offset1:231
	s_waitcnt lgkmcnt(4)
	v_cvt_pk_bf16_f32 v170, v244, v245
	v_cvt_pk_bf16_f32 v171, v246, v247
	v_cvt_pk_bf16_f32 v172, v248, v249
	v_cvt_pk_bf16_f32 v173, v250, v251
	global_store_dwordx4 v62, v[170:173], s[28:29]
	ds_read2_b32 v[244:245], v56 offset0:0 offset1:33
	ds_read2_b32 v[246:247], v56 offset0:66 offset1:99
	ds_read2_b32 v[248:249], v56 offset0:132 offset1:165
	ds_read2_b32 v[250:251], v56 offset0:198 offset1:231
	s_waitcnt lgkmcnt(4)
	v_cvt_pk_bf16_f32 v176, v38, v39
	v_cvt_pk_bf16_f32 v177, v40, v41
	v_cvt_pk_bf16_f32 v178, v42, v43
	v_cvt_pk_bf16_f32 v179, v44, v45
	global_store_dwordx4 v63, v[176:179], s[28:29]
	ds_read2_b32 v[38:39], v57 offset0:0 offset1:33
	ds_read2_b32 v[40:41], v57 offset0:66 offset1:99
	ds_read2_b32 v[42:43], v57 offset0:132 offset1:165
	ds_read2_b32 v[44:45], v57 offset0:198 offset1:231
	s_waitcnt lgkmcnt(4)
	v_cvt_pk_bf16_f32 v170, v244, v245
	v_cvt_pk_bf16_f32 v171, v246, v247
	v_cvt_pk_bf16_f32 v172, v248, v249
	v_cvt_pk_bf16_f32 v173, v250, v251
	global_store_dwordx4 v64, v[170:173], s[28:29]
	ds_read2_b32 v[244:245], v58 offset0:0 offset1:33
	ds_read2_b32 v[246:247], v58 offset0:66 offset1:99
	ds_read2_b32 v[248:249], v58 offset0:132 offset1:165
	ds_read2_b32 v[250:251], v58 offset0:198 offset1:231
	s_waitcnt lgkmcnt(4)
	v_cvt_pk_bf16_f32 v176, v38, v39
	v_cvt_pk_bf16_f32 v177, v40, v41
	v_cvt_pk_bf16_f32 v178, v42, v43
	v_cvt_pk_bf16_f32 v179, v44, v45
	global_store_dwordx4 v65, v[176:179], s[28:29]
	ds_read2_b32 v[38:39], v59 offset0:0 offset1:33
	ds_read2_b32 v[40:41], v59 offset0:66 offset1:99
	ds_read2_b32 v[42:43], v59 offset0:132 offset1:165
	ds_read2_b32 v[44:45], v59 offset0:198 offset1:231
	s_waitcnt lgkmcnt(4)
	v_cvt_pk_bf16_f32 v170, v244, v245
	v_cvt_pk_bf16_f32 v171, v246, v247
	v_cvt_pk_bf16_f32 v172, v248, v249
	v_cvt_pk_bf16_f32 v173, v250, v251
	global_store_dwordx4 v66, v[170:173], s[28:29]
	s_waitcnt lgkmcnt(0)
	v_cvt_pk_bf16_f32 v176, v38, v39
	v_cvt_pk_bf16_f32 v177, v40, v41
	v_cvt_pk_bf16_f32 v178, v42, v43
	v_cvt_pk_bf16_f32 v179, v44, v45
	global_store_dwordx4 v67, v[176:179], s[28:29]
.Ldfr_done:
	s_mov_b64 exec, s[34:35]
